# mixer epilogues: gate loads widened too (dwordx4 + v_permlane32_swap back to the MFMA row layout)
# speedup vs baseline: 1.0295x; 1.0030x over previous
.Lpool_xdma_done0:
	v_readlane_b32 s54, v250, 23
	v_readlane_b32 s55, v250, 24
	v_mov_b32_e32 v2, v45
	v_mov_b32_e32 v3, 0
	s_add_i32 s43, s48, 0x1a000
	v_lshl_add_u64 v[4:5], s[54:55], 0, v[2:3]
	s_mov_b32 m0, s43
	s_nop 0
	global_load_lds_dwordx4 v[4:5], off
	v_and_b32_e32 v94, 32, v216
	v_lshrrev_b32_e32 v94, 2, v94
	v_mov_b32_e32 v95, 0
	v_lshl_add_u64 v[96:97], v[10:11], 0, v[94:95]
	v_lshl_add_u64 v[98:99], s[52:53], 0, v[96:97]
	global_load_dwordx4 v[12:15], v[98:99], off offset:0
	global_load_dwordx4 v[16:19], v[98:99], off offset:32
	global_load_dwordx4 v[20:23], v[98:99], off offset:64
	global_load_dwordx4 v[24:27], v[98:99], off offset:96
	s_waitcnt vmcnt(4)
	s_barrier
	s_add_u32 s46, s44, 0x80
	s_addc_u32 s47, s45, 0
	s_add_i32 s43, s48, 0x8800
	v_lshl_add_u64 v[4:5], s[46:47], 0, v[6:7]
	s_mov_b32 m0, s43
	s_nop 0
	global_load_lds_dwordx4 v[4:5], off
	s_add_u32 s46, s44, 0x8080
	s_addc_u32 s47, s45, 0
	s_add_i32 s43, s48, 0xa800
	v_lshl_add_u64 v[4:5], s[46:47], 0, v[6:7]
	s_mov_b32 m0, s43
	s_nop 0
	global_load_lds_dwordx4 v[4:5], off
	s_add_u32 s46, s44, 0x10080
	s_addc_u32 s47, s45, 0
	s_add_i32 s43, s48, 0xc800
	v_lshl_add_u64 v[4:5], s[46:47], 0, v[6:7]
	s_mov_b32 m0, s43
	s_nop 0
	global_load_lds_dwordx4 v[4:5], off
	s_add_u32 s46, s44, 0x18080
	s_addc_u32 s47, s45, 0
	s_add_i32 s43, s48, 0xe800
	v_lshl_add_u64 v[4:5], s[46:47], 0, v[6:7]
	s_mov_b32 m0, s43
	s_nop 0
	global_load_lds_dwordx4 v[4:5], off
	s_cmp_lt_u32 s41, 2
	s_cbranch_scc0 .Lpool_xdma_done1
	s_add_u32 s46, s44, 0x20080
	s_addc_u32 s47, s45, 0
	s_add_i32 s43, s48, 0x10800
	v_lshl_add_u64 v[4:5], s[46:47], 0, v[6:7]
	s_mov_b32 m0, s43
	s_nop 0
	global_load_lds_dwordx4 v[4:5], off

.Lpool_nz0:
	v_add_f32_e32 v93, v61, v60
	s_cmp_eq_u32 s42, 1
	s_cselect_b32 s51, 0x3f800000, s50
	v_fma_f32 v2, v93, s51, -v61
	v_add_f32_e32 v93, v93, v62
	v_sub_f32_e32 v93, v93, v60
	v_fma_f32 v3, v93, s50, -v62
	v_cvt_pk_bf16_f32 v2, v2, v3
	ds_write_b16 v9, v2 offset:0
	ds_write_b16_d16_hi v9, v2 offset:144
	v_add_f32_e32 v93, v93, v63
	v_sub_f32_e32 v93, v93, v61
	v_fma_f32 v4, v93, s50, -v63
	v_add_f32_e32 v93, v93, v64
	v_sub_f32_e32 v93, v93, v62
	v_fma_f32 v5, v93, s50, -v64
	v_cvt_pk_bf16_f32 v4, v4, v5
	ds_write_b16 v9, v4 offset:288
	ds_write_b16_d16_hi v9, v4 offset:432
	v_add_f32_e32 v93, v93, v65
	v_sub_f32_e32 v93, v93, v63
	v_fma_f32 v2, v93, s50, -v65
	v_add_f32_e32 v93, v93, v66
	v_sub_f32_e32 v93, v93, v64
	v_fma_f32 v3, v93, s50, -v66
	v_cvt_pk_bf16_f32 v2, v2, v3
	ds_write_b16 v9, v2 offset:576
	ds_write_b16_d16_hi v9, v2 offset:720
	v_add_f32_e32 v93, v93, v67
	v_sub_f32_e32 v93, v93, v65
	v_fma_f32 v4, v93, s50, -v67
	v_add_f32_e32 v93, v93, v68
	v_sub_f32_e32 v93, v93, v66
	v_fma_f32 v5, v93, s50, -v68
	v_cvt_pk_bf16_f32 v4, v4, v5
	ds_write_b16 v9, v4 offset:864
	ds_write_b16_d16_hi v9, v4 offset:1008
	v_add_f32_e32 v93, v93, v69
	v_sub_f32_e32 v93, v93, v67
	v_fma_f32 v2, v93, s50, -v69
	v_add_f32_e32 v93, v93, v70
	v_sub_f32_e32 v93, v93, v68
	v_fma_f32 v3, v93, s50, -v70
	v_cvt_pk_bf16_f32 v2, v2, v3
	ds_write_b16 v9, v2 offset:1152
	ds_write_b16_d16_hi v9, v2 offset:1296
	v_add_f32_e32 v93, v93, v71
	v_sub_f32_e32 v93, v93, v69
	v_fma_f32 v4, v93, s50, -v71
	v_add_f32_e32 v93, v93, v72
	v_sub_f32_e32 v93, v93, v70
	v_fma_f32 v5, v93, s50, -v72
	v_cvt_pk_bf16_f32 v4, v4, v5
	ds_write_b16 v9, v4 offset:1440
	ds_write_b16_d16_hi v9, v4 offset:1584
	v_add_f32_e32 v93, v93, v73
	v_sub_f32_e32 v93, v93, v71
	v_fma_f32 v2, v93, s50, -v73
	v_add_f32_e32 v93, v93, v74
	v_sub_f32_e32 v93, v93, v72
	v_fma_f32 v3, v93, s50, -v74
	v_cvt_pk_bf16_f32 v2, v2, v3
	ds_write_b16 v9, v2 offset:1728
	ds_write_b16_d16_hi v9, v2 offset:1872
	v_add_f32_e32 v93, v93, v75
	v_sub_f32_e32 v93, v93, v73
	v_fma_f32 v4, v93, s50, -v75
	v_add_f32_e32 v93, v93, v76
	v_sub_f32_e32 v93, v93, v74
	v_fma_f32 v5, v93, s50, -v76
	v_cvt_pk_bf16_f32 v4, v4, v5
	ds_write_b16 v9, v4 offset:2016
	ds_write_b16_d16_hi v9, v4 offset:2160
	v_add_f32_e32 v93, v93, v77
	v_sub_f32_e32 v93, v93, v75
	v_fma_f32 v2, v93, s50, -v77
	v_add_f32_e32 v93, v93, v78
	v_sub_f32_e32 v93, v93, v76
	v_fma_f32 v3, v93, s50, -v78
	v_cvt_pk_bf16_f32 v2, v2, v3
	ds_write_b16 v9, v2 offset:2304
	ds_write_b16_d16_hi v9, v2 offset:2448
	v_add_f32_e32 v93, v93, v79
	v_sub_f32_e32 v93, v93, v77
	v_fma_f32 v4, v93, s50, -v79
	v_add_f32_e32 v93, v93, v80
	v_sub_f32_e32 v93, v93, v78
	v_fma_f32 v5, v93, s50, -v80
	v_cvt_pk_bf16_f32 v4, v4, v5
	ds_write_b16 v9, v4 offset:2592
	ds_write_b16_d16_hi v9, v4 offset:2736
	v_add_f32_e32 v93, v93, v81
	v_sub_f32_e32 v93, v93, v79
	v_fma_f32 v2, v93, s50, -v81
	v_add_f32_e32 v93, v93, v82
	v_sub_f32_e32 v93, v93, v80
	v_fma_f32 v3, v93, s50, -v82
	v_cvt_pk_bf16_f32 v2, v2, v3
	ds_write_b16 v9, v2 offset:2880
	ds_write_b16_d16_hi v9, v2 offset:3024
	v_add_f32_e32 v93, v93, v83
	v_sub_f32_e32 v93, v93, v81
	v_fma_f32 v4, v93, s50, -v83
	v_add_f32_e32 v93, v93, v84
	v_sub_f32_e32 v93, v93, v82
	v_fma_f32 v5, v93, s50, -v84
	v_cvt_pk_bf16_f32 v4, v4, v5
	ds_write_b16 v9, v4 offset:3168
	ds_write_b16_d16_hi v9, v4 offset:3312
	v_add_f32_e32 v93, v93, v85
	v_sub_f32_e32 v93, v93, v83
	v_fma_f32 v2, v93, s50, -v85
	v_add_f32_e32 v93, v93, v86
	v_sub_f32_e32 v93, v93, v84
	v_fma_f32 v3, v93, s50, -v86
	v_cvt_pk_bf16_f32 v2, v2, v3
	ds_write_b16 v9, v2 offset:3456
	ds_write_b16_d16_hi v9, v2 offset:3600
	v_add_f32_e32 v93, v93, v87
	v_sub_f32_e32 v93, v93, v85
	v_fma_f32 v4, v93, s50, -v87
	v_add_f32_e32 v93, v93, v88
	v_sub_f32_e32 v93, v93, v86
	v_fma_f32 v5, v93, s50, -v88
	v_cvt_pk_bf16_f32 v4, v4, v5
	ds_write_b16 v9, v4 offset:3744
	ds_write_b16_d16_hi v9, v4 offset:3888
	v_add_f32_e32 v93, v93, v89
	v_sub_f32_e32 v93, v93, v87
	v_fma_f32 v2, v93, s50, -v89
	v_add_f32_e32 v93, v93, v90
	v_sub_f32_e32 v93, v93, v88
	v_fma_f32 v3, v93, s50, -v90
	v_cvt_pk_bf16_f32 v2, v2, v3
	ds_write_b16 v9, v2 offset:4032
	ds_write_b16_d16_hi v9, v2 offset:4176
	v_add_f32_e32 v93, v93, v91
	v_sub_f32_e32 v93, v93, v89
	v_fma_f32 v4, v93, s50, -v91
	v_add_f32_e32 v93, v93, v92
	v_sub_f32_e32 v93, v93, v90
	v_fma_f32 v5, v93, s50, -v92
	v_cvt_pk_bf16_f32 v4, v4, v5
	ds_write_b16 v9, v4 offset:4320
	ds_write_b16_d16_hi v9, v4 offset:4464
	v_and_b32_e32 v2, 31, v0
	v_lshrrev_b32_e32 v3, 5, v0
	v_bfe_u32 v4, v0, 1, 3
	v_xor_b32_e32 v3, v3, v4
	v_lshlrev_b32_e32 v2, 7, v2
	v_add_u32_e32 v2, 0x1a000, v2
	v_lshl_add_u32 v5, v3, 4, v2
	v_xor_b32_e32 v4, 2, v3
	v_lshl_add_u32 v4, v4, 4, v2
	v_xor_b32_e32 v88, 4, v3
	v_xor_b32_e32 v3, 6, v3
	v_lshl_add_u32 v3, v3, 4, v2
	v_lshl_add_u32 v2, v88, 4, v2
	s_waitcnt lgkmcnt(0)
	ds_read_b128 v[28:31], v5 offset:0
	ds_read_b128 v[32:35], v5 offset:4096
	ds_read_b128 v[78:81], v44 offset:0
	ds_read_b128 v[82:85], v44 offset:32
	ds_read_b128 v[86:89], v44 offset:64
	ds_read_b128 v[90:93], v44 offset:96
	ds_read_b128 v[36:39], v4 offset:0
	ds_read_b128 v[40:43], v4 offset:4096
	s_waitcnt lgkmcnt(0)
	v_mfma_f32_32x32x16_bf16 v[46:61], v[28:31], v[78:81], 0
	v_mfma_f32_32x32x16_bf16 v[62:77], v[32:35], v[78:81], 0
	ds_read_b128 v[28:31], v2 offset:0
	ds_read_b128 v[32:35], v2 offset:4096
	v_mfma_f32_32x32x16_bf16 v[46:61], v[36:39], v[82:85], v[46:61]
	v_mfma_f32_32x32x16_bf16 v[62:77], v[40:43], v[82:85], v[62:77]
	ds_read_b128 v[36:39], v3 offset:0
	ds_read_b128 v[40:43], v3 offset:4096
	s_waitcnt lgkmcnt(2)
	v_mfma_f32_32x32x16_bf16 v[46:61], v[28:31], v[86:89], v[46:61]
	v_mfma_f32_32x32x16_bf16 v[62:77], v[32:35], v[86:89], v[62:77]
	s_waitcnt lgkmcnt(0)
	v_mfma_f32_32x32x16_bf16 v[46:61], v[36:39], v[90:93], v[46:61]
	v_mfma_f32_32x32x16_bf16 v[62:77], v[40:43], v[90:93], v[62:77]
	v_lshl_add_u64 v[4:5], s[52:53], 0, v[10:11]
	v_lshl_add_u64 v[98:99], s[52:53], 0, v[96:97]
	s_nop 14
	s_waitcnt vmcnt(5)
	v_permlane32_swap_b32 v12, v14
	v_permlane32_swap_b32 v13, v15
	v_permlane32_swap_b32 v16, v18
	v_permlane32_swap_b32 v17, v19
	v_permlane32_swap_b32 v20, v22
	v_permlane32_swap_b32 v21, v23
	v_permlane32_swap_b32 v24, v26
	v_permlane32_swap_b32 v25, v27
	s_mov_b32 s56, 0xbfb8aa3b
	s_mov_b32 s57, 0xbfb8aa3b
	s_mov_b32 s54, 1.0
	s_mov_b32 s55, 1.0
	v_lshlrev_b32_e32 v78, 16, v12
	v_and_b32_e32 v79, 0xffff0000, v12
	v_lshlrev_b32_e32 v80, 16, v13
	v_and_b32_e32 v81, 0xffff0000, v13
	v_lshlrev_b32_e32 v82, 16, v14
	v_and_b32_e32 v83, 0xffff0000, v14
	v_lshlrev_b32_e32 v84, 16, v15
	v_and_b32_e32 v85, 0xffff0000, v15
	v_lshlrev_b32_e32 v86, 16, v16
	v_and_b32_e32 v87, 0xffff0000, v16
	v_lshlrev_b32_e32 v88, 16, v17
	v_and_b32_e32 v89, 0xffff0000, v17
	v_lshlrev_b32_e32 v90, 16, v18
	v_and_b32_e32 v91, 0xffff0000, v18
	v_lshlrev_b32_e32 v92, 16, v19
	v_and_b32_e32 v93, 0xffff0000, v19
	v_pk_mul_f32 v[28:29], v[78:79], s[56:57]
	v_pk_mul_f32 v[30:31], v[80:81], s[56:57]
	v_pk_mul_f32 v[32:33], v[82:83], s[56:57]
	v_pk_mul_f32 v[34:35], v[84:85], s[56:57]
	v_pk_mul_f32 v[36:37], v[86:87], s[56:57]
	v_pk_mul_f32 v[38:39], v[88:89], s[56:57]
	v_pk_mul_f32 v[40:41], v[90:91], s[56:57]
	v_pk_mul_f32 v[42:43], v[92:93], s[56:57]
	v_exp_f32_e32 v28, v28
	v_exp_f32_e32 v29, v29
	v_exp_f32_e32 v30, v30
	v_exp_f32_e32 v31, v31
	v_exp_f32_e32 v32, v32
	v_exp_f32_e32 v33, v33
	v_exp_f32_e32 v34, v34
	v_exp_f32_e32 v35, v35
	v_exp_f32_e32 v36, v36
	v_exp_f32_e32 v37, v37
	v_exp_f32_e32 v38, v38
	v_exp_f32_e32 v39, v39
	v_exp_f32_e32 v40, v40
	v_exp_f32_e32 v41, v41
	v_exp_f32_e32 v42, v42
	v_exp_f32_e32 v43, v43
	v_pk_add_f32 v[28:29], v[28:29], s[54:55]
	v_pk_add_f32 v[30:31], v[30:31], s[54:55]
	v_pk_add_f32 v[32:33], v[32:33], s[54:55]
	v_pk_add_f32 v[34:35], v[34:35], s[54:55]
	v_pk_add_f32 v[36:37], v[36:37], s[54:55]
	v_pk_add_f32 v[38:39], v[38:39], s[54:55]
	v_pk_add_f32 v[40:41], v[40:41], s[54:55]
	v_pk_add_f32 v[42:43], v[42:43], s[54:55]
	v_rcp_f32_e32 v28, v28
	v_rcp_f32_e32 v29, v29
	v_rcp_f32_e32 v30, v30
	v_rcp_f32_e32 v31, v31
	v_rcp_f32_e32 v32, v32
	v_rcp_f32_e32 v33, v33
	v_rcp_f32_e32 v34, v34
	v_rcp_f32_e32 v35, v35
	v_rcp_f32_e32 v36, v36
	v_rcp_f32_e32 v37, v37
	v_rcp_f32_e32 v38, v38
	v_rcp_f32_e32 v39, v39
	v_rcp_f32_e32 v40, v40
	v_rcp_f32_e32 v41, v41
	v_rcp_f32_e32 v42, v42
	v_rcp_f32_e32 v43, v43
	v_pk_mul_f32 v[28:29], v[78:79], v[28:29]
	v_pk_mul_f32 v[30:31], v[80:81], v[30:31]
	v_pk_mul_f32 v[32:33], v[82:83], v[32:33]
	v_pk_mul_f32 v[34:35], v[84:85], v[34:35]
	v_pk_mul_f32 v[36:37], v[86:87], v[36:37]
	v_pk_mul_f32 v[38:39], v[88:89], v[38:39]
	v_pk_mul_f32 v[40:41], v[90:91], v[40:41]
	v_pk_mul_f32 v[42:43], v[92:93], v[42:43]
	v_pk_mul_f32 v[28:29], v[46:47], v[28:29]
	v_pk_mul_f32 v[30:31], v[48:49], v[30:31]
	v_pk_mul_f32 v[32:33], v[50:51], v[32:33]
	v_pk_mul_f32 v[34:35], v[52:53], v[34:35]
	v_pk_mul_f32 v[36:37], v[54:55], v[36:37]
	v_pk_mul_f32 v[38:39], v[56:57], v[38:39]
	v_pk_mul_f32 v[40:41], v[58:59], v[40:41]
	v_pk_mul_f32 v[42:43], v[60:61], v[42:43]
	v_cvt_pk_bf16_f32 v78, v28, v29
	v_cvt_pk_bf16_f32 v79, v30, v31
	v_cvt_pk_bf16_f32 v80, v32, v33
	v_cvt_pk_bf16_f32 v81, v34, v35
	v_cvt_pk_bf16_f32 v82, v36, v37
	v_cvt_pk_bf16_f32 v83, v38, v39
	v_cvt_pk_bf16_f32 v84, v40, v41
	v_cvt_pk_bf16_f32 v85, v42, v43
	s_nop 1
	v_permlane32_swap_b32 v78, v80
	v_permlane32_swap_b32 v79, v81
	v_permlane32_swap_b32 v82, v84
	v_permlane32_swap_b32 v83, v85
	global_store_dwordx4 v[98:99], v[78:81], off offset:0
	global_store_dwordx4 v[98:99], v[82:85], off offset:32
	s_nop 1
	v_lshlrev_b32_e32 v78, 16, v20
	v_and_b32_e32 v79, 0xffff0000, v20
	v_lshlrev_b32_e32 v80, 16, v21
	v_and_b32_e32 v81, 0xffff0000, v21
	v_lshlrev_b32_e32 v82, 16, v22
	v_and_b32_e32 v83, 0xffff0000, v22
	v_lshlrev_b32_e32 v84, 16, v23
	v_and_b32_e32 v85, 0xffff0000, v23
	v_lshlrev_b32_e32 v86, 16, v24
	v_and_b32_e32 v87, 0xffff0000, v24
	v_lshlrev_b32_e32 v88, 16, v25
	v_and_b32_e32 v89, 0xffff0000, v25
	v_lshlrev_b32_e32 v90, 16, v26
	v_and_b32_e32 v91, 0xffff0000, v26
	v_lshlrev_b32_e32 v92, 16, v27
	v_and_b32_e32 v93, 0xffff0000, v27
	v_pk_mul_f32 v[28:29], v[78:79], s[56:57]
	v_pk_mul_f32 v[30:31], v[80:81], s[56:57]
	v_pk_mul_f32 v[32:33], v[82:83], s[56:57]
	v_pk_mul_f32 v[34:35], v[84:85], s[56:57]
	v_pk_mul_f32 v[36:37], v[86:87], s[56:57]
	v_pk_mul_f32 v[38:39], v[88:89], s[56:57]
	v_pk_mul_f32 v[40:41], v[90:91], s[56:57]
	v_pk_mul_f32 v[42:43], v[92:93], s[56:57]
	v_exp_f32_e32 v28, v28
	v_exp_f32_e32 v29, v29
	v_exp_f32_e32 v30, v30
	v_exp_f32_e32 v31, v31
	v_exp_f32_e32 v32, v32
	v_exp_f32_e32 v33, v33
	v_exp_f32_e32 v34, v34
	v_exp_f32_e32 v35, v35
	v_exp_f32_e32 v36, v36
	v_exp_f32_e32 v37, v37
	v_exp_f32_e32 v38, v38
	v_exp_f32_e32 v39, v39
	v_exp_f32_e32 v40, v40
	v_exp_f32_e32 v41, v41
	v_exp_f32_e32 v42, v42
	v_exp_f32_e32 v43, v43
	v_pk_add_f32 v[28:29], v[28:29], s[54:55]
	v_pk_add_f32 v[30:31], v[30:31], s[54:55]
	v_pk_add_f32 v[32:33], v[32:33], s[54:55]
	v_pk_add_f32 v[34:35], v[34:35], s[54:55]
	v_pk_add_f32 v[36:37], v[36:37], s[54:55]
	v_pk_add_f32 v[38:39], v[38:39], s[54:55]
	v_pk_add_f32 v[40:41], v[40:41], s[54:55]
	v_pk_add_f32 v[42:43], v[42:43], s[54:55]
	v_rcp_f32_e32 v28, v28
	v_rcp_f32_e32 v29, v29
	v_rcp_f32_e32 v30, v30
	v_rcp_f32_e32 v31, v31
	v_rcp_f32_e32 v32, v32
	v_rcp_f32_e32 v33, v33
	v_rcp_f32_e32 v34, v34
	v_rcp_f32_e32 v35, v35
	v_rcp_f32_e32 v36, v36
	v_rcp_f32_e32 v37, v37
	v_rcp_f32_e32 v38, v38
	v_rcp_f32_e32 v39, v39
	v_rcp_f32_e32 v40, v40
	v_rcp_f32_e32 v41, v41
	v_rcp_f32_e32 v42, v42
	v_rcp_f32_e32 v43, v43
	v_pk_mul_f32 v[28:29], v[78:79], v[28:29]
	v_pk_mul_f32 v[30:31], v[80:81], v[30:31]
	v_pk_mul_f32 v[32:33], v[82:83], v[32:33]
	v_pk_mul_f32 v[34:35], v[84:85], v[34:35]
	v_pk_mul_f32 v[36:37], v[86:87], v[36:37]
	v_pk_mul_f32 v[38:39], v[88:89], v[38:39]
	v_pk_mul_f32 v[40:41], v[90:91], v[40:41]
	v_pk_mul_f32 v[42:43], v[92:93], v[42:43]
	v_pk_mul_f32 v[28:29], v[62:63], v[28:29]
	v_pk_mul_f32 v[30:31], v[64:65], v[30:31]
	v_pk_mul_f32 v[32:33], v[66:67], v[32:33]
	v_pk_mul_f32 v[34:35], v[68:69], v[34:35]
	v_pk_mul_f32 v[36:37], v[70:71], v[36:37]
	v_pk_mul_f32 v[38:39], v[72:73], v[38:39]
	v_pk_mul_f32 v[40:41], v[74:75], v[40:41]
	v_pk_mul_f32 v[42:43], v[76:77], v[42:43]
	v_cvt_pk_bf16_f32 v78, v28, v29
	v_cvt_pk_bf16_f32 v79, v30, v31
	v_cvt_pk_bf16_f32 v80, v32, v33
	v_cvt_pk_bf16_f32 v81, v34, v35
	v_cvt_pk_bf16_f32 v82, v36, v37
	v_cvt_pk_bf16_f32 v83, v38, v39
	v_cvt_pk_bf16_f32 v84, v40, v41
	v_cvt_pk_bf16_f32 v85, v42, v43
	s_nop 1
	v_permlane32_swap_b32 v78, v80
	v_permlane32_swap_b32 v79, v81
	v_permlane32_swap_b32 v82, v84
	v_permlane32_swap_b32 v83, v85
	global_store_dwordx4 v[98:99], v[78:81], off offset:64
	global_store_dwordx4 v[98:99], v[82:85], off offset:96
	v_lshl_add_u64 v[98:99], s[52:53], 0, v[96:97]
	global_load_dwordx4 v[12:15], v[98:99], off offset:128
	global_load_dwordx4 v[16:19], v[98:99], off offset:160
	global_load_dwordx4 v[20:23], v[98:99], off offset:192
	global_load_dwordx4 v[24:27], v[98:99], off offset:224
	s_waitcnt vmcnt(4)
	s_barrier
	s_add_u32 s46, s44, 0x100
	s_addc_u32 s47, s45, 0
	s_add_i32 s43, s48, 0x0
	v_lshl_add_u64 v[4:5], s[46:47], 0, v[6:7]
	s_mov_b32 m0, s43
	s_nop 0
	global_load_lds_dwordx4 v[4:5], off
	s_add_u32 s46, s44, 0x8100
	s_addc_u32 s47, s45, 0
	s_add_i32 s43, s48, 0x2000
	v_lshl_add_u64 v[4:5], s[46:47], 0, v[6:7]
	s_mov_b32 m0, s43
	s_nop 0
	global_load_lds_dwordx4 v[4:5], off
	s_add_u32 s46, s44, 0x10100
	s_addc_u32 s47, s45, 0
	s_add_i32 s43, s48, 0x4000
	v_lshl_add_u64 v[4:5], s[46:47], 0, v[6:7]
	s_mov_b32 m0, s43
	s_nop 0
	global_load_lds_dwordx4 v[4:5], off
	s_add_u32 s46, s44, 0x18100
	s_addc_u32 s47, s45, 0
	s_add_i32 s43, s48, 0x6000
	v_lshl_add_u64 v[4:5], s[46:47], 0, v[6:7]
	s_mov_b32 m0, s43
	s_nop 0
	global_load_lds_dwordx4 v[4:5], off
	s_cmp_lt_u32 s41, 2
	s_cbranch_scc0 .Lpool_xdma_done2
	s_add_u32 s46, s44, 0x20100
	s_addc_u32 s47, s45, 0
	s_add_i32 s43, s48, 0x8000
	v_lshl_add_u64 v[4:5], s[46:47], 0, v[6:7]
	s_mov_b32 m0, s43
	s_nop 0
	global_load_lds_dwordx4 v[4:5], off

.Lpool_nz1:
	v_add_f32_e32 v93, v61, v60
	v_add_f32_e32 v93, v93, v59
	v_add_f32_e32 v93, v93, v58
	s_cmp_eq_u32 s42, 1
	s_cselect_b32 s51, 0x3f800000, s50
	v_fma_f32 v2, v93, s51, -v61
	v_add_f32_e32 v93, v93, v62
	v_sub_f32_e32 v93, v93, v58
	s_cmp_eq_u32 s42, 1
	s_cselect_b32 s51, 0x3f000000, s50
	v_fma_f32 v3, v93, s51, -v62
	v_cvt_pk_bf16_f32 v2, v2, v3
	ds_write_b16 v9, v2 offset:0
	ds_write_b16_d16_hi v9, v2 offset:144
	v_add_f32_e32 v93, v93, v63
	v_sub_f32_e32 v93, v93, v59
	s_cmp_eq_u32 s42, 1
	s_cselect_b32 s51, 0x3eaaaaab, s50
	v_fma_f32 v4, v93, s51, -v63
	v_add_f32_e32 v93, v93, v64
	v_sub_f32_e32 v93, v93, v60
	v_fma_f32 v5, v93, s50, -v64
	v_cvt_pk_bf16_f32 v4, v4, v5
	ds_write_b16 v9, v4 offset:288
	ds_write_b16_d16_hi v9, v4 offset:432
	v_add_f32_e32 v93, v93, v65
	v_sub_f32_e32 v93, v93, v61
	v_fma_f32 v2, v93, s50, -v65
	v_add_f32_e32 v93, v93, v66
	v_sub_f32_e32 v93, v93, v62
	v_fma_f32 v3, v93, s50, -v66
	v_cvt_pk_bf16_f32 v2, v2, v3
	ds_write_b16 v9, v2 offset:576
	ds_write_b16_d16_hi v9, v2 offset:720
	v_add_f32_e32 v93, v93, v67
	v_sub_f32_e32 v93, v93, v63
	v_fma_f32 v4, v93, s50, -v67
	v_add_f32_e32 v93, v93, v68
	v_sub_f32_e32 v93, v93, v64
	v_fma_f32 v5, v93, s50, -v68
	v_cvt_pk_bf16_f32 v4, v4, v5
	ds_write_b16 v9, v4 offset:864
	ds_write_b16_d16_hi v9, v4 offset:1008
	v_add_f32_e32 v93, v93, v69
	v_sub_f32_e32 v93, v93, v65
	v_fma_f32 v2, v93, s50, -v69
	v_add_f32_e32 v93, v93, v70
	v_sub_f32_e32 v93, v93, v66
	v_fma_f32 v3, v93, s50, -v70
	v_cvt_pk_bf16_f32 v2, v2, v3
	ds_write_b16 v9, v2 offset:1152
	ds_write_b16_d16_hi v9, v2 offset:1296
	v_add_f32_e32 v93, v93, v71
	v_sub_f32_e32 v93, v93, v67
	v_fma_f32 v4, v93, s50, -v71
	v_add_f32_e32 v93, v93, v72
	v_sub_f32_e32 v93, v93, v68
	v_fma_f32 v5, v93, s50, -v72
	v_cvt_pk_bf16_f32 v4, v4, v5
	ds_write_b16 v9, v4 offset:1440
	ds_write_b16_d16_hi v9, v4 offset:1584
	v_add_f32_e32 v93, v93, v73
	v_sub_f32_e32 v93, v93, v69
	v_fma_f32 v2, v93, s50, -v73
	v_add_f32_e32 v93, v93, v74
	v_sub_f32_e32 v93, v93, v70
	v_fma_f32 v3, v93, s50, -v74
	v_cvt_pk_bf16_f32 v2, v2, v3
	ds_write_b16 v9, v2 offset:1728
	ds_write_b16_d16_hi v9, v2 offset:1872
	v_add_f32_e32 v93, v93, v75
	v_sub_f32_e32 v93, v93, v71
	v_fma_f32 v4, v93, s50, -v75
	v_add_f32_e32 v93, v93, v76
	v_sub_f32_e32 v93, v93, v72
	v_fma_f32 v5, v93, s50, -v76
	v_cvt_pk_bf16_f32 v4, v4, v5
	ds_write_b16 v9, v4 offset:2016
	ds_write_b16_d16_hi v9, v4 offset:2160
	v_add_f32_e32 v93, v93, v77
	v_sub_f32_e32 v93, v93, v73
	v_fma_f32 v2, v93, s50, -v77
	v_add_f32_e32 v93, v93, v78
	v_sub_f32_e32 v93, v93, v74
	v_fma_f32 v3, v93, s50, -v78
	v_cvt_pk_bf16_f32 v2, v2, v3
	ds_write_b16 v9, v2 offset:2304
	ds_write_b16_d16_hi v9, v2 offset:2448
	v_add_f32_e32 v93, v93, v79
	v_sub_f32_e32 v93, v93, v75
	v_fma_f32 v4, v93, s50, -v79
	v_add_f32_e32 v93, v93, v80
	v_sub_f32_e32 v93, v93, v76
	v_fma_f32 v5, v93, s50, -v80
	v_cvt_pk_bf16_f32 v4, v4, v5
	ds_write_b16 v9, v4 offset:2592
	ds_write_b16_d16_hi v9, v4 offset:2736
	v_add_f32_e32 v93, v93, v81
	v_sub_f32_e32 v93, v93, v77
	v_fma_f32 v2, v93, s50, -v81
	v_add_f32_e32 v93, v93, v82
	v_sub_f32_e32 v93, v93, v78
	v_fma_f32 v3, v93, s50, -v82
	v_cvt_pk_bf16_f32 v2, v2, v3
	ds_write_b16 v9, v2 offset:2880
	ds_write_b16_d16_hi v9, v2 offset:3024
	v_add_f32_e32 v93, v93, v83
	v_sub_f32_e32 v93, v93, v79
	v_fma_f32 v4, v93, s50, -v83
	v_add_f32_e32 v93, v93, v84
	v_sub_f32_e32 v93, v93, v80
	v_fma_f32 v5, v93, s50, -v84
	v_cvt_pk_bf16_f32 v4, v4, v5
	ds_write_b16 v9, v4 offset:3168
	ds_write_b16_d16_hi v9, v4 offset:3312
	v_add_f32_e32 v93, v93, v85
	v_sub_f32_e32 v93, v93, v81
	v_fma_f32 v2, v93, s50, -v85
	v_add_f32_e32 v93, v93, v86
	v_sub_f32_e32 v93, v93, v82
	v_fma_f32 v3, v93, s50, -v86
	v_cvt_pk_bf16_f32 v2, v2, v3
	ds_write_b16 v9, v2 offset:3456
	ds_write_b16_d16_hi v9, v2 offset:3600
	v_add_f32_e32 v93, v93, v87
	v_sub_f32_e32 v93, v93, v83
	v_fma_f32 v4, v93, s50, -v87
	v_add_f32_e32 v93, v93, v88
	v_sub_f32_e32 v93, v93, v84
	v_fma_f32 v5, v93, s50, -v88
	v_cvt_pk_bf16_f32 v4, v4, v5
	ds_write_b16 v9, v4 offset:3744
	ds_write_b16_d16_hi v9, v4 offset:3888
	v_add_f32_e32 v93, v93, v89
	v_sub_f32_e32 v93, v93, v85
	v_fma_f32 v2, v93, s50, -v89
	v_add_f32_e32 v93, v93, v90
	v_sub_f32_e32 v93, v93, v86
	v_fma_f32 v3, v93, s50, -v90
	v_cvt_pk_bf16_f32 v2, v2, v3
	ds_write_b16 v9, v2 offset:4032
	ds_write_b16_d16_hi v9, v2 offset:4176
	v_add_f32_e32 v93, v93, v91
	v_sub_f32_e32 v93, v93, v87
	v_fma_f32 v4, v93, s50, -v91
	v_add_f32_e32 v93, v93, v92
	v_sub_f32_e32 v93, v93, v88
	v_fma_f32 v5, v93, s50, -v92
	v_cvt_pk_bf16_f32 v4, v4, v5
	ds_write_b16 v9, v4 offset:4320
	ds_write_b16_d16_hi v9, v4 offset:4464
	v_and_b32_e32 v2, 31, v0
	v_lshrrev_b32_e32 v3, 5, v0
	v_bfe_u32 v4, v0, 1, 3
	v_xor_b32_e32 v3, v3, v4
	v_lshlrev_b32_e32 v2, 7, v2
	v_add_u32_e32 v2, 0x1c000, v2
	v_lshl_add_u32 v5, v3, 4, v2
	v_xor_b32_e32 v4, 2, v3
	v_lshl_add_u32 v4, v4, 4, v2
	v_xor_b32_e32 v88, 4, v3
	v_xor_b32_e32 v3, 6, v3
	v_lshl_add_u32 v3, v3, 4, v2
	v_lshl_add_u32 v2, v88, 4, v2
	s_waitcnt lgkmcnt(0)
	ds_read_b128 v[28:31], v5 offset:0
	ds_read_b128 v[32:35], v5 offset:4096
	ds_read_b128 v[78:81], v44 offset:0
	ds_read_b128 v[82:85], v44 offset:32
	ds_read_b128 v[86:89], v44 offset:64
	ds_read_b128 v[90:93], v44 offset:96
	ds_read_b128 v[36:39], v4 offset:0
	ds_read_b128 v[40:43], v4 offset:4096
	s_waitcnt lgkmcnt(0)
	v_mfma_f32_32x32x16_bf16 v[46:61], v[28:31], v[78:81], 0
	v_mfma_f32_32x32x16_bf16 v[62:77], v[32:35], v[78:81], 0
	ds_read_b128 v[28:31], v2 offset:0
	ds_read_b128 v[32:35], v2 offset:4096
	v_mfma_f32_32x32x16_bf16 v[46:61], v[36:39], v[82:85], v[46:61]
	v_mfma_f32_32x32x16_bf16 v[62:77], v[40:43], v[82:85], v[62:77]
	ds_read_b128 v[36:39], v3 offset:0
	ds_read_b128 v[40:43], v3 offset:4096
	s_waitcnt lgkmcnt(2)
	v_mfma_f32_32x32x16_bf16 v[46:61], v[28:31], v[86:89], v[46:61]
	v_mfma_f32_32x32x16_bf16 v[62:77], v[32:35], v[86:89], v[62:77]
	s_waitcnt lgkmcnt(0)
	v_mfma_f32_32x32x16_bf16 v[46:61], v[36:39], v[90:93], v[46:61]
	v_mfma_f32_32x32x16_bf16 v[62:77], v[40:43], v[90:93], v[62:77]
	v_lshl_add_u64 v[4:5], s[52:53], 0, v[10:11]
	v_lshl_add_u64 v[98:99], s[52:53], 0, v[96:97]
	s_nop 14
	s_waitcnt vmcnt(5)
	v_permlane32_swap_b32 v12, v14
	v_permlane32_swap_b32 v13, v15
	v_permlane32_swap_b32 v16, v18
	v_permlane32_swap_b32 v17, v19
	v_permlane32_swap_b32 v20, v22
	v_permlane32_swap_b32 v21, v23
	v_permlane32_swap_b32 v24, v26
	v_permlane32_swap_b32 v25, v27
	s_mov_b32 s56, 0xbfb8aa3b
	s_mov_b32 s57, 0xbfb8aa3b
	s_mov_b32 s54, 1.0
	s_mov_b32 s55, 1.0
	v_lshlrev_b32_e32 v78, 16, v12
	v_and_b32_e32 v79, 0xffff0000, v12
	v_lshlrev_b32_e32 v80, 16, v13
	v_and_b32_e32 v81, 0xffff0000, v13
	v_lshlrev_b32_e32 v82, 16, v14
	v_and_b32_e32 v83, 0xffff0000, v14
	v_lshlrev_b32_e32 v84, 16, v15
	v_and_b32_e32 v85, 0xffff0000, v15
	v_lshlrev_b32_e32 v86, 16, v16
	v_and_b32_e32 v87, 0xffff0000, v16
	v_lshlrev_b32_e32 v88, 16, v17
	v_and_b32_e32 v89, 0xffff0000, v17
	v_lshlrev_b32_e32 v90, 16, v18
	v_and_b32_e32 v91, 0xffff0000, v18
	v_lshlrev_b32_e32 v92, 16, v19
	v_and_b32_e32 v93, 0xffff0000, v19
	v_pk_mul_f32 v[28:29], v[78:79], s[56:57]
	v_pk_mul_f32 v[30:31], v[80:81], s[56:57]
	v_pk_mul_f32 v[32:33], v[82:83], s[56:57]
	v_pk_mul_f32 v[34:35], v[84:85], s[56:57]
	v_pk_mul_f32 v[36:37], v[86:87], s[56:57]
	v_pk_mul_f32 v[38:39], v[88:89], s[56:57]
	v_pk_mul_f32 v[40:41], v[90:91], s[56:57]
	v_pk_mul_f32 v[42:43], v[92:93], s[56:57]
	v_exp_f32_e32 v28, v28
	v_exp_f32_e32 v29, v29
	v_exp_f32_e32 v30, v30
	v_exp_f32_e32 v31, v31
	v_exp_f32_e32 v32, v32
	v_exp_f32_e32 v33, v33
	v_exp_f32_e32 v34, v34
	v_exp_f32_e32 v35, v35
	v_exp_f32_e32 v36, v36
	v_exp_f32_e32 v37, v37
	v_exp_f32_e32 v38, v38
	v_exp_f32_e32 v39, v39
	v_exp_f32_e32 v40, v40
	v_exp_f32_e32 v41, v41
	v_exp_f32_e32 v42, v42
	v_exp_f32_e32 v43, v43
	v_pk_add_f32 v[28:29], v[28:29], s[54:55]
	v_pk_add_f32 v[30:31], v[30:31], s[54:55]
	v_pk_add_f32 v[32:33], v[32:33], s[54:55]
	v_pk_add_f32 v[34:35], v[34:35], s[54:55]
	v_pk_add_f32 v[36:37], v[36:37], s[54:55]
	v_pk_add_f32 v[38:39], v[38:39], s[54:55]
	v_pk_add_f32 v[40:41], v[40:41], s[54:55]
	v_pk_add_f32 v[42:43], v[42:43], s[54:55]
	v_rcp_f32_e32 v28, v28
	v_rcp_f32_e32 v29, v29
	v_rcp_f32_e32 v30, v30
	v_rcp_f32_e32 v31, v31
	v_rcp_f32_e32 v32, v32
	v_rcp_f32_e32 v33, v33
	v_rcp_f32_e32 v34, v34
	v_rcp_f32_e32 v35, v35
	v_rcp_f32_e32 v36, v36
	v_rcp_f32_e32 v37, v37
	v_rcp_f32_e32 v38, v38
	v_rcp_f32_e32 v39, v39
	v_rcp_f32_e32 v40, v40
	v_rcp_f32_e32 v41, v41
	v_rcp_f32_e32 v42, v42
	v_rcp_f32_e32 v43, v43
	v_pk_mul_f32 v[28:29], v[78:79], v[28:29]
	v_pk_mul_f32 v[30:31], v[80:81], v[30:31]
	v_pk_mul_f32 v[32:33], v[82:83], v[32:33]
	v_pk_mul_f32 v[34:35], v[84:85], v[34:35]
	v_pk_mul_f32 v[36:37], v[86:87], v[36:37]
	v_pk_mul_f32 v[38:39], v[88:89], v[38:39]
	v_pk_mul_f32 v[40:41], v[90:91], v[40:41]
	v_pk_mul_f32 v[42:43], v[92:93], v[42:43]
	v_pk_mul_f32 v[28:29], v[46:47], v[28:29]
	v_pk_mul_f32 v[30:31], v[48:49], v[30:31]
	v_pk_mul_f32 v[32:33], v[50:51], v[32:33]
	v_pk_mul_f32 v[34:35], v[52:53], v[34:35]
	v_pk_mul_f32 v[36:37], v[54:55], v[36:37]
	v_pk_mul_f32 v[38:39], v[56:57], v[38:39]
	v_pk_mul_f32 v[40:41], v[58:59], v[40:41]
	v_pk_mul_f32 v[42:43], v[60:61], v[42:43]
	v_cvt_pk_bf16_f32 v78, v28, v29
	v_cvt_pk_bf16_f32 v79, v30, v31
	v_cvt_pk_bf16_f32 v80, v32, v33
	v_cvt_pk_bf16_f32 v81, v34, v35
	v_cvt_pk_bf16_f32 v82, v36, v37
	v_cvt_pk_bf16_f32 v83, v38, v39
	v_cvt_pk_bf16_f32 v84, v40, v41
	v_cvt_pk_bf16_f32 v85, v42, v43
	s_nop 1
	v_permlane32_swap_b32 v78, v80
	v_permlane32_swap_b32 v79, v81
	v_permlane32_swap_b32 v82, v84
	v_permlane32_swap_b32 v83, v85
	global_store_dwordx4 v[98:99], v[78:81], off offset:128
	global_store_dwordx4 v[98:99], v[82:85], off offset:160
	s_nop 1
	v_lshlrev_b32_e32 v78, 16, v20
	v_and_b32_e32 v79, 0xffff0000, v20
	v_lshlrev_b32_e32 v80, 16, v21
	v_and_b32_e32 v81, 0xffff0000, v21
	v_lshlrev_b32_e32 v82, 16, v22
	v_and_b32_e32 v83, 0xffff0000, v22
	v_lshlrev_b32_e32 v84, 16, v23
	v_and_b32_e32 v85, 0xffff0000, v23
	v_lshlrev_b32_e32 v86, 16, v24
	v_and_b32_e32 v87, 0xffff0000, v24
	v_lshlrev_b32_e32 v88, 16, v25
	v_and_b32_e32 v89, 0xffff0000, v25
	v_lshlrev_b32_e32 v90, 16, v26
	v_and_b32_e32 v91, 0xffff0000, v26
	v_lshlrev_b32_e32 v92, 16, v27
	v_and_b32_e32 v93, 0xffff0000, v27
	v_pk_mul_f32 v[28:29], v[78:79], s[56:57]
	v_pk_mul_f32 v[30:31], v[80:81], s[56:57]
	v_pk_mul_f32 v[32:33], v[82:83], s[56:57]
	v_pk_mul_f32 v[34:35], v[84:85], s[56:57]
	v_pk_mul_f32 v[36:37], v[86:87], s[56:57]
	v_pk_mul_f32 v[38:39], v[88:89], s[56:57]
	v_pk_mul_f32 v[40:41], v[90:91], s[56:57]
	v_pk_mul_f32 v[42:43], v[92:93], s[56:57]
	v_exp_f32_e32 v28, v28
	v_exp_f32_e32 v29, v29
	v_exp_f32_e32 v30, v30
	v_exp_f32_e32 v31, v31
	v_exp_f32_e32 v32, v32
	v_exp_f32_e32 v33, v33
	v_exp_f32_e32 v34, v34
	v_exp_f32_e32 v35, v35
	v_exp_f32_e32 v36, v36
	v_exp_f32_e32 v37, v37
	v_exp_f32_e32 v38, v38
	v_exp_f32_e32 v39, v39
	v_exp_f32_e32 v40, v40
	v_exp_f32_e32 v41, v41
	v_exp_f32_e32 v42, v42
	v_exp_f32_e32 v43, v43
	v_pk_add_f32 v[28:29], v[28:29], s[54:55]
	v_pk_add_f32 v[30:31], v[30:31], s[54:55]
	v_pk_add_f32 v[32:33], v[32:33], s[54:55]
	v_pk_add_f32 v[34:35], v[34:35], s[54:55]
	v_pk_add_f32 v[36:37], v[36:37], s[54:55]
	v_pk_add_f32 v[38:39], v[38:39], s[54:55]
	v_pk_add_f32 v[40:41], v[40:41], s[54:55]
	v_pk_add_f32 v[42:43], v[42:43], s[54:55]
	v_rcp_f32_e32 v28, v28
	v_rcp_f32_e32 v29, v29
	v_rcp_f32_e32 v30, v30
	v_rcp_f32_e32 v31, v31
	v_rcp_f32_e32 v32, v32
	v_rcp_f32_e32 v33, v33
	v_rcp_f32_e32 v34, v34
	v_rcp_f32_e32 v35, v35
	v_rcp_f32_e32 v36, v36
	v_rcp_f32_e32 v37, v37
	v_rcp_f32_e32 v38, v38
	v_rcp_f32_e32 v39, v39
	v_rcp_f32_e32 v40, v40
	v_rcp_f32_e32 v41, v41
	v_rcp_f32_e32 v42, v42
	v_rcp_f32_e32 v43, v43
	v_pk_mul_f32 v[28:29], v[78:79], v[28:29]
	v_pk_mul_f32 v[30:31], v[80:81], v[30:31]
	v_pk_mul_f32 v[32:33], v[82:83], v[32:33]
	v_pk_mul_f32 v[34:35], v[84:85], v[34:35]
	v_pk_mul_f32 v[36:37], v[86:87], v[36:37]
	v_pk_mul_f32 v[38:39], v[88:89], v[38:39]
	v_pk_mul_f32 v[40:41], v[90:91], v[40:41]
	v_pk_mul_f32 v[42:43], v[92:93], v[42:43]
	v_pk_mul_f32 v[28:29], v[62:63], v[28:29]
	v_pk_mul_f32 v[30:31], v[64:65], v[30:31]
	v_pk_mul_f32 v[32:33], v[66:67], v[32:33]
	v_pk_mul_f32 v[34:35], v[68:69], v[34:35]
	v_pk_mul_f32 v[36:37], v[70:71], v[36:37]
	v_pk_mul_f32 v[38:39], v[72:73], v[38:39]
	v_pk_mul_f32 v[40:41], v[74:75], v[40:41]
	v_pk_mul_f32 v[42:43], v[76:77], v[42:43]
	v_cvt_pk_bf16_f32 v78, v28, v29
	v_cvt_pk_bf16_f32 v79, v30, v31
	v_cvt_pk_bf16_f32 v80, v32, v33
	v_cvt_pk_bf16_f32 v81, v34, v35
	v_cvt_pk_bf16_f32 v82, v36, v37
	v_cvt_pk_bf16_f32 v83, v38, v39
	v_cvt_pk_bf16_f32 v84, v40, v41
	v_cvt_pk_bf16_f32 v85, v42, v43
	s_nop 1
	v_permlane32_swap_b32 v78, v80
	v_permlane32_swap_b32 v79, v81
	v_permlane32_swap_b32 v82, v84
	v_permlane32_swap_b32 v83, v85
	global_store_dwordx4 v[98:99], v[78:81], off offset:192
	global_store_dwordx4 v[98:99], v[82:85], off offset:224
	v_lshl_add_u64 v[98:99], s[52:53], 0, v[96:97]
	global_load_dwordx4 v[12:15], v[98:99], off offset:256
	global_load_dwordx4 v[16:19], v[98:99], off offset:288
	global_load_dwordx4 v[20:23], v[98:99], off offset:320
	global_load_dwordx4 v[24:27], v[98:99], off offset:352
	s_waitcnt vmcnt(4)
	s_barrier
	s_add_u32 s46, s44, 0x180
	s_addc_u32 s47, s45, 0
	s_add_i32 s43, s48, 0x8800
	v_lshl_add_u64 v[4:5], s[46:47], 0, v[6:7]
	s_mov_b32 m0, s43
	s_nop 0
	global_load_lds_dwordx4 v[4:5], off
	s_add_u32 s46, s44, 0x8180
	s_addc_u32 s47, s45, 0
	s_add_i32 s43, s48, 0xa800
	v_lshl_add_u64 v[4:5], s[46:47], 0, v[6:7]
	s_mov_b32 m0, s43
	s_nop 0
	global_load_lds_dwordx4 v[4:5], off
	s_add_u32 s46, s44, 0x10180
	s_addc_u32 s47, s45, 0
	s_add_i32 s43, s48, 0xc800
	v_lshl_add_u64 v[4:5], s[46:47], 0, v[6:7]
	s_mov_b32 m0, s43
	s_nop 0
	global_load_lds_dwordx4 v[4:5], off
	s_add_u32 s46, s44, 0x18180
	s_addc_u32 s47, s45, 0
	s_add_i32 s43, s48, 0xe800
	v_lshl_add_u64 v[4:5], s[46:47], 0, v[6:7]
	s_mov_b32 m0, s43
	s_nop 0
	global_load_lds_dwordx4 v[4:5], off
	s_cmp_lt_u32 s41, 2
	s_cbranch_scc0 .Lpool_xdma_done3
	s_add_u32 s46, s44, 0x20180
	s_addc_u32 s47, s45, 0
	s_add_i32 s43, s48, 0x10800
	v_lshl_add_u64 v[4:5], s[46:47], 0, v[6:7]
	s_mov_b32 m0, s43
	s_nop 0
	global_load_lds_dwordx4 v[4:5], off

.Lpool_nz2:
	v_add_f32_e32 v93, v61, v60
	v_add_f32_e32 v93, v93, v59
	v_add_f32_e32 v93, v93, v58
	v_add_f32_e32 v93, v93, v57
	v_add_f32_e32 v93, v93, v56
	v_add_f32_e32 v93, v93, v55
	v_add_f32_e32 v93, v93, v54
	s_cmp_eq_u32 s42, 1
	s_cselect_b32 s51, 0x3f800000, s50
	v_fma_f32 v2, v93, s51, -v61
	v_add_f32_e32 v93, v93, v62
	v_sub_f32_e32 v93, v93, v54
	s_cmp_eq_u32 s42, 1
	s_cselect_b32 s51, 0x3f000000, s50
	v_fma_f32 v3, v93, s51, -v62
	v_cvt_pk_bf16_f32 v2, v2, v3
	ds_write_b16 v9, v2 offset:0
	ds_write_b16_d16_hi v9, v2 offset:144
	v_add_f32_e32 v93, v93, v63
	v_sub_f32_e32 v93, v93, v55
	s_cmp_eq_u32 s42, 1
	s_cselect_b32 s51, 0x3eaaaaab, s50
	v_fma_f32 v4, v93, s51, -v63
	v_add_f32_e32 v93, v93, v64
	v_sub_f32_e32 v93, v93, v56
	s_cmp_eq_u32 s42, 1
	s_cselect_b32 s51, 0x3e800000, s50
	v_fma_f32 v5, v93, s51, -v64
	v_cvt_pk_bf16_f32 v4, v4, v5
	ds_write_b16 v9, v4 offset:288
	ds_write_b16_d16_hi v9, v4 offset:432
	v_add_f32_e32 v93, v93, v65
	v_sub_f32_e32 v93, v93, v57
	s_cmp_eq_u32 s42, 1
	s_cselect_b32 s51, 0x3e4ccccd, s50
	v_fma_f32 v2, v93, s51, -v65
	v_add_f32_e32 v93, v93, v66
	v_sub_f32_e32 v93, v93, v58
	s_cmp_eq_u32 s42, 1
	s_cselect_b32 s51, 0x3e2aaaab, s50
	v_fma_f32 v3, v93, s51, -v66
	v_cvt_pk_bf16_f32 v2, v2, v3
	ds_write_b16 v9, v2 offset:576
	ds_write_b16_d16_hi v9, v2 offset:720
	v_add_f32_e32 v93, v93, v67
	v_sub_f32_e32 v93, v93, v59
	s_cmp_eq_u32 s42, 1
	s_cselect_b32 s51, 0x3e124925, s50
	v_fma_f32 v4, v93, s51, -v67
	v_add_f32_e32 v93, v93, v68
	v_sub_f32_e32 v93, v93, v60
	v_fma_f32 v5, v93, s50, -v68
	v_cvt_pk_bf16_f32 v4, v4, v5
	ds_write_b16 v9, v4 offset:864
	ds_write_b16_d16_hi v9, v4 offset:1008
	v_add_f32_e32 v93, v93, v69
	v_sub_f32_e32 v93, v93, v61
	v_fma_f32 v2, v93, s50, -v69
	v_add_f32_e32 v93, v93, v70
	v_sub_f32_e32 v93, v93, v62
	v_fma_f32 v3, v93, s50, -v70
	v_cvt_pk_bf16_f32 v2, v2, v3
	ds_write_b16 v9, v2 offset:1152
	ds_write_b16_d16_hi v9, v2 offset:1296
	v_add_f32_e32 v93, v93, v71
	v_sub_f32_e32 v93, v93, v63
	v_fma_f32 v4, v93, s50, -v71
	v_add_f32_e32 v93, v93, v72
	v_sub_f32_e32 v93, v93, v64
	v_fma_f32 v5, v93, s50, -v72
	v_cvt_pk_bf16_f32 v4, v4, v5
	ds_write_b16 v9, v4 offset:1440
	ds_write_b16_d16_hi v9, v4 offset:1584
	v_add_f32_e32 v93, v93, v73
	v_sub_f32_e32 v93, v93, v65
	v_fma_f32 v2, v93, s50, -v73
	v_add_f32_e32 v93, v93, v74
	v_sub_f32_e32 v93, v93, v66
	v_fma_f32 v3, v93, s50, -v74
	v_cvt_pk_bf16_f32 v2, v2, v3
	ds_write_b16 v9, v2 offset:1728
	ds_write_b16_d16_hi v9, v2 offset:1872
	v_add_f32_e32 v93, v93, v75
	v_sub_f32_e32 v93, v93, v67
	v_fma_f32 v4, v93, s50, -v75
	v_add_f32_e32 v93, v93, v76
	v_sub_f32_e32 v93, v93, v68
	v_fma_f32 v5, v93, s50, -v76
	v_cvt_pk_bf16_f32 v4, v4, v5
	ds_write_b16 v9, v4 offset:2016
	ds_write_b16_d16_hi v9, v4 offset:2160
	v_add_f32_e32 v93, v93, v77
	v_sub_f32_e32 v93, v93, v69
	v_fma_f32 v2, v93, s50, -v77
	v_add_f32_e32 v93, v93, v78
	v_sub_f32_e32 v93, v93, v70
	v_fma_f32 v3, v93, s50, -v78
	v_cvt_pk_bf16_f32 v2, v2, v3
	ds_write_b16 v9, v2 offset:2304
	ds_write_b16_d16_hi v9, v2 offset:2448
	v_add_f32_e32 v93, v93, v79
	v_sub_f32_e32 v93, v93, v71
	v_fma_f32 v4, v93, s50, -v79
	v_add_f32_e32 v93, v93, v80
	v_sub_f32_e32 v93, v93, v72
	v_fma_f32 v5, v93, s50, -v80
	v_cvt_pk_bf16_f32 v4, v4, v5
	ds_write_b16 v9, v4 offset:2592
	ds_write_b16_d16_hi v9, v4 offset:2736
	v_add_f32_e32 v93, v93, v81
	v_sub_f32_e32 v93, v93, v73
	v_fma_f32 v2, v93, s50, -v81
	v_add_f32_e32 v93, v93, v82
	v_sub_f32_e32 v93, v93, v74
	v_fma_f32 v3, v93, s50, -v82
	v_cvt_pk_bf16_f32 v2, v2, v3
	ds_write_b16 v9, v2 offset:2880
	ds_write_b16_d16_hi v9, v2 offset:3024
	v_add_f32_e32 v93, v93, v83
	v_sub_f32_e32 v93, v93, v75
	v_fma_f32 v4, v93, s50, -v83
	v_add_f32_e32 v93, v93, v84
	v_sub_f32_e32 v93, v93, v76
	v_fma_f32 v5, v93, s50, -v84
	v_cvt_pk_bf16_f32 v4, v4, v5
	ds_write_b16 v9, v4 offset:3168
	ds_write_b16_d16_hi v9, v4 offset:3312
	v_add_f32_e32 v93, v93, v85
	v_sub_f32_e32 v93, v93, v77
	v_fma_f32 v2, v93, s50, -v85
	v_add_f32_e32 v93, v93, v86
	v_sub_f32_e32 v93, v93, v78
	v_fma_f32 v3, v93, s50, -v86
	v_cvt_pk_bf16_f32 v2, v2, v3
	ds_write_b16 v9, v2 offset:3456
	ds_write_b16_d16_hi v9, v2 offset:3600
	v_add_f32_e32 v93, v93, v87
	v_sub_f32_e32 v93, v93, v79
	v_fma_f32 v4, v93, s50, -v87
	v_add_f32_e32 v93, v93, v88
	v_sub_f32_e32 v93, v93, v80
	v_fma_f32 v5, v93, s50, -v88
	v_cvt_pk_bf16_f32 v4, v4, v5
	ds_write_b16 v9, v4 offset:3744
	ds_write_b16_d16_hi v9, v4 offset:3888
	v_add_f32_e32 v93, v93, v89
	v_sub_f32_e32 v93, v93, v81
	v_fma_f32 v2, v93, s50, -v89
	v_add_f32_e32 v93, v93, v90
	v_sub_f32_e32 v93, v93, v82
	v_fma_f32 v3, v93, s50, -v90
	v_cvt_pk_bf16_f32 v2, v2, v3
	ds_write_b16 v9, v2 offset:4032
	ds_write_b16_d16_hi v9, v2 offset:4176
	v_add_f32_e32 v93, v93, v91
	v_sub_f32_e32 v93, v93, v83
	v_fma_f32 v4, v93, s50, -v91
	v_add_f32_e32 v93, v93, v92
	v_sub_f32_e32 v93, v93, v84
	v_fma_f32 v5, v93, s50, -v92
	v_cvt_pk_bf16_f32 v4, v4, v5
	ds_write_b16 v9, v4 offset:4320
	ds_write_b16_d16_hi v9, v4 offset:4464
	v_and_b32_e32 v2, 31, v0
	v_lshrrev_b32_e32 v3, 5, v0
	v_bfe_u32 v4, v0, 1, 3
	v_xor_b32_e32 v3, v3, v4
	v_lshlrev_b32_e32 v2, 7, v2
	v_add_u32_e32 v2, 0x1a000, v2
	v_lshl_add_u32 v5, v3, 4, v2
	v_xor_b32_e32 v4, 2, v3
	v_lshl_add_u32 v4, v4, 4, v2
	v_xor_b32_e32 v88, 4, v3
	v_xor_b32_e32 v3, 6, v3
	v_lshl_add_u32 v3, v3, 4, v2
	v_lshl_add_u32 v2, v88, 4, v2
	s_waitcnt lgkmcnt(0)
	ds_read_b128 v[28:31], v5 offset:0
	ds_read_b128 v[32:35], v5 offset:4096
	ds_read_b128 v[78:81], v44 offset:0
	ds_read_b128 v[82:85], v44 offset:32
	ds_read_b128 v[86:89], v44 offset:64
	ds_read_b128 v[90:93], v44 offset:96
	ds_read_b128 v[36:39], v4 offset:0
	ds_read_b128 v[40:43], v4 offset:4096
	s_waitcnt lgkmcnt(0)
	v_mfma_f32_32x32x16_bf16 v[46:61], v[28:31], v[78:81], 0
	v_mfma_f32_32x32x16_bf16 v[62:77], v[32:35], v[78:81], 0
	ds_read_b128 v[28:31], v2 offset:0
	ds_read_b128 v[32:35], v2 offset:4096
	v_mfma_f32_32x32x16_bf16 v[46:61], v[36:39], v[82:85], v[46:61]
	v_mfma_f32_32x32x16_bf16 v[62:77], v[40:43], v[82:85], v[62:77]
	ds_read_b128 v[36:39], v3 offset:0
	ds_read_b128 v[40:43], v3 offset:4096
	s_waitcnt lgkmcnt(2)
	v_mfma_f32_32x32x16_bf16 v[46:61], v[28:31], v[86:89], v[46:61]
	v_mfma_f32_32x32x16_bf16 v[62:77], v[32:35], v[86:89], v[62:77]
	s_waitcnt lgkmcnt(0)
	v_mfma_f32_32x32x16_bf16 v[46:61], v[36:39], v[90:93], v[46:61]
	v_mfma_f32_32x32x16_bf16 v[62:77], v[40:43], v[90:93], v[62:77]
	v_lshl_add_u64 v[4:5], s[52:53], 0, v[10:11]
	v_lshl_add_u64 v[98:99], s[52:53], 0, v[96:97]
	s_nop 14
	s_waitcnt vmcnt(5)
	v_permlane32_swap_b32 v12, v14
	v_permlane32_swap_b32 v13, v15
	v_permlane32_swap_b32 v16, v18
	v_permlane32_swap_b32 v17, v19
	v_permlane32_swap_b32 v20, v22
	v_permlane32_swap_b32 v21, v23
	v_permlane32_swap_b32 v24, v26
	v_permlane32_swap_b32 v25, v27
	s_mov_b32 s56, 0xbfb8aa3b
	s_mov_b32 s57, 0xbfb8aa3b
	s_mov_b32 s54, 1.0
	s_mov_b32 s55, 1.0
	v_lshlrev_b32_e32 v78, 16, v12
	v_and_b32_e32 v79, 0xffff0000, v12
	v_lshlrev_b32_e32 v80, 16, v13
	v_and_b32_e32 v81, 0xffff0000, v13
	v_lshlrev_b32_e32 v82, 16, v14
	v_and_b32_e32 v83, 0xffff0000, v14
	v_lshlrev_b32_e32 v84, 16, v15
	v_and_b32_e32 v85, 0xffff0000, v15
	v_lshlrev_b32_e32 v86, 16, v16
	v_and_b32_e32 v87, 0xffff0000, v16
	v_lshlrev_b32_e32 v88, 16, v17
	v_and_b32_e32 v89, 0xffff0000, v17
	v_lshlrev_b32_e32 v90, 16, v18
	v_and_b32_e32 v91, 0xffff0000, v18
	v_lshlrev_b32_e32 v92, 16, v19
	v_and_b32_e32 v93, 0xffff0000, v19
	v_pk_mul_f32 v[28:29], v[78:79], s[56:57]
	v_pk_mul_f32 v[30:31], v[80:81], s[56:57]
	v_pk_mul_f32 v[32:33], v[82:83], s[56:57]
	v_pk_mul_f32 v[34:35], v[84:85], s[56:57]
	v_pk_mul_f32 v[36:37], v[86:87], s[56:57]
	v_pk_mul_f32 v[38:39], v[88:89], s[56:57]
	v_pk_mul_f32 v[40:41], v[90:91], s[56:57]
	v_pk_mul_f32 v[42:43], v[92:93], s[56:57]
	v_exp_f32_e32 v28, v28
	v_exp_f32_e32 v29, v29
	v_exp_f32_e32 v30, v30
	v_exp_f32_e32 v31, v31
	v_exp_f32_e32 v32, v32
	v_exp_f32_e32 v33, v33
	v_exp_f32_e32 v34, v34
	v_exp_f32_e32 v35, v35
	v_exp_f32_e32 v36, v36
	v_exp_f32_e32 v37, v37
	v_exp_f32_e32 v38, v38
	v_exp_f32_e32 v39, v39
	v_exp_f32_e32 v40, v40
	v_exp_f32_e32 v41, v41
	v_exp_f32_e32 v42, v42
	v_exp_f32_e32 v43, v43
	v_pk_add_f32 v[28:29], v[28:29], s[54:55]
	v_pk_add_f32 v[30:31], v[30:31], s[54:55]
	v_pk_add_f32 v[32:33], v[32:33], s[54:55]
	v_pk_add_f32 v[34:35], v[34:35], s[54:55]
	v_pk_add_f32 v[36:37], v[36:37], s[54:55]
	v_pk_add_f32 v[38:39], v[38:39], s[54:55]
	v_pk_add_f32 v[40:41], v[40:41], s[54:55]
	v_pk_add_f32 v[42:43], v[42:43], s[54:55]
	v_rcp_f32_e32 v28, v28
	v_rcp_f32_e32 v29, v29
	v_rcp_f32_e32 v30, v30
	v_rcp_f32_e32 v31, v31
	v_rcp_f32_e32 v32, v32
	v_rcp_f32_e32 v33, v33
	v_rcp_f32_e32 v34, v34
	v_rcp_f32_e32 v35, v35
	v_rcp_f32_e32 v36, v36
	v_rcp_f32_e32 v37, v37
	v_rcp_f32_e32 v38, v38
	v_rcp_f32_e32 v39, v39
	v_rcp_f32_e32 v40, v40
	v_rcp_f32_e32 v41, v41
	v_rcp_f32_e32 v42, v42
	v_rcp_f32_e32 v43, v43
	v_pk_mul_f32 v[28:29], v[78:79], v[28:29]
	v_pk_mul_f32 v[30:31], v[80:81], v[30:31]
	v_pk_mul_f32 v[32:33], v[82:83], v[32:33]
	v_pk_mul_f32 v[34:35], v[84:85], v[34:35]
	v_pk_mul_f32 v[36:37], v[86:87], v[36:37]
	v_pk_mul_f32 v[38:39], v[88:89], v[38:39]
	v_pk_mul_f32 v[40:41], v[90:91], v[40:41]
	v_pk_mul_f32 v[42:43], v[92:93], v[42:43]
	v_pk_mul_f32 v[28:29], v[46:47], v[28:29]
	v_pk_mul_f32 v[30:31], v[48:49], v[30:31]
	v_pk_mul_f32 v[32:33], v[50:51], v[32:33]
	v_pk_mul_f32 v[34:35], v[52:53], v[34:35]
	v_pk_mul_f32 v[36:37], v[54:55], v[36:37]
	v_pk_mul_f32 v[38:39], v[56:57], v[38:39]
	v_pk_mul_f32 v[40:41], v[58:59], v[40:41]
	v_pk_mul_f32 v[42:43], v[60:61], v[42:43]
	v_cvt_pk_bf16_f32 v78, v28, v29
	v_cvt_pk_bf16_f32 v79, v30, v31
	v_cvt_pk_bf16_f32 v80, v32, v33
	v_cvt_pk_bf16_f32 v81, v34, v35
	v_cvt_pk_bf16_f32 v82, v36, v37
	v_cvt_pk_bf16_f32 v83, v38, v39
	v_cvt_pk_bf16_f32 v84, v40, v41
	v_cvt_pk_bf16_f32 v85, v42, v43
	s_nop 1
	v_permlane32_swap_b32 v78, v80
	v_permlane32_swap_b32 v79, v81
	v_permlane32_swap_b32 v82, v84
	v_permlane32_swap_b32 v83, v85
	global_store_dwordx4 v[98:99], v[78:81], off offset:256
	global_store_dwordx4 v[98:99], v[82:85], off offset:288
	s_nop 1
	v_lshlrev_b32_e32 v78, 16, v20
	v_and_b32_e32 v79, 0xffff0000, v20
	v_lshlrev_b32_e32 v80, 16, v21
	v_and_b32_e32 v81, 0xffff0000, v21
	v_lshlrev_b32_e32 v82, 16, v22
	v_and_b32_e32 v83, 0xffff0000, v22
	v_lshlrev_b32_e32 v84, 16, v23
	v_and_b32_e32 v85, 0xffff0000, v23
	v_lshlrev_b32_e32 v86, 16, v24
	v_and_b32_e32 v87, 0xffff0000, v24
	v_lshlrev_b32_e32 v88, 16, v25
	v_and_b32_e32 v89, 0xffff0000, v25
	v_lshlrev_b32_e32 v90, 16, v26
	v_and_b32_e32 v91, 0xffff0000, v26
	v_lshlrev_b32_e32 v92, 16, v27
	v_and_b32_e32 v93, 0xffff0000, v27
	v_pk_mul_f32 v[28:29], v[78:79], s[56:57]
	v_pk_mul_f32 v[30:31], v[80:81], s[56:57]
	v_pk_mul_f32 v[32:33], v[82:83], s[56:57]
	v_pk_mul_f32 v[34:35], v[84:85], s[56:57]
	v_pk_mul_f32 v[36:37], v[86:87], s[56:57]
	v_pk_mul_f32 v[38:39], v[88:89], s[56:57]
	v_pk_mul_f32 v[40:41], v[90:91], s[56:57]
	v_pk_mul_f32 v[42:43], v[92:93], s[56:57]
	v_exp_f32_e32 v28, v28
	v_exp_f32_e32 v29, v29
	v_exp_f32_e32 v30, v30
	v_exp_f32_e32 v31, v31
	v_exp_f32_e32 v32, v32
	v_exp_f32_e32 v33, v33
	v_exp_f32_e32 v34, v34
	v_exp_f32_e32 v35, v35
	v_exp_f32_e32 v36, v36
	v_exp_f32_e32 v37, v37
	v_exp_f32_e32 v38, v38
	v_exp_f32_e32 v39, v39
	v_exp_f32_e32 v40, v40
	v_exp_f32_e32 v41, v41
	v_exp_f32_e32 v42, v42
	v_exp_f32_e32 v43, v43
	v_pk_add_f32 v[28:29], v[28:29], s[54:55]
	v_pk_add_f32 v[30:31], v[30:31], s[54:55]
	v_pk_add_f32 v[32:33], v[32:33], s[54:55]
	v_pk_add_f32 v[34:35], v[34:35], s[54:55]
	v_pk_add_f32 v[36:37], v[36:37], s[54:55]
	v_pk_add_f32 v[38:39], v[38:39], s[54:55]
	v_pk_add_f32 v[40:41], v[40:41], s[54:55]
	v_pk_add_f32 v[42:43], v[42:43], s[54:55]
	v_rcp_f32_e32 v28, v28
	v_rcp_f32_e32 v29, v29
	v_rcp_f32_e32 v30, v30
	v_rcp_f32_e32 v31, v31
	v_rcp_f32_e32 v32, v32
	v_rcp_f32_e32 v33, v33
	v_rcp_f32_e32 v34, v34
	v_rcp_f32_e32 v35, v35
	v_rcp_f32_e32 v36, v36
	v_rcp_f32_e32 v37, v37
	v_rcp_f32_e32 v38, v38
	v_rcp_f32_e32 v39, v39
	v_rcp_f32_e32 v40, v40
	v_rcp_f32_e32 v41, v41
	v_rcp_f32_e32 v42, v42
	v_rcp_f32_e32 v43, v43
	v_pk_mul_f32 v[28:29], v[78:79], v[28:29]
	v_pk_mul_f32 v[30:31], v[80:81], v[30:31]
	v_pk_mul_f32 v[32:33], v[82:83], v[32:33]
	v_pk_mul_f32 v[34:35], v[84:85], v[34:35]
	v_pk_mul_f32 v[36:37], v[86:87], v[36:37]
	v_pk_mul_f32 v[38:39], v[88:89], v[38:39]
	v_pk_mul_f32 v[40:41], v[90:91], v[40:41]
	v_pk_mul_f32 v[42:43], v[92:93], v[42:43]
	v_pk_mul_f32 v[28:29], v[62:63], v[28:29]
	v_pk_mul_f32 v[30:31], v[64:65], v[30:31]
	v_pk_mul_f32 v[32:33], v[66:67], v[32:33]
	v_pk_mul_f32 v[34:35], v[68:69], v[34:35]
	v_pk_mul_f32 v[36:37], v[70:71], v[36:37]
	v_pk_mul_f32 v[38:39], v[72:73], v[38:39]
	v_pk_mul_f32 v[40:41], v[74:75], v[40:41]
	v_pk_mul_f32 v[42:43], v[76:77], v[42:43]
	v_cvt_pk_bf16_f32 v78, v28, v29
	v_cvt_pk_bf16_f32 v79, v30, v31
	v_cvt_pk_bf16_f32 v80, v32, v33
	v_cvt_pk_bf16_f32 v81, v34, v35
	v_cvt_pk_bf16_f32 v82, v36, v37
	v_cvt_pk_bf16_f32 v83, v38, v39
	v_cvt_pk_bf16_f32 v84, v40, v41
	v_cvt_pk_bf16_f32 v85, v42, v43
	s_nop 1
	v_permlane32_swap_b32 v78, v80
	v_permlane32_swap_b32 v79, v81
	v_permlane32_swap_b32 v82, v84
	v_permlane32_swap_b32 v83, v85
	global_store_dwordx4 v[98:99], v[78:81], off offset:320
	global_store_dwordx4 v[98:99], v[82:85], off offset:352
	v_lshl_add_u64 v[98:99], s[52:53], 0, v[96:97]
	global_load_dwordx4 v[12:15], v[98:99], off offset:384
	global_load_dwordx4 v[16:19], v[98:99], off offset:416
	global_load_dwordx4 v[20:23], v[98:99], off offset:448
	global_load_dwordx4 v[24:27], v[98:99], off offset:480
	s_waitcnt vmcnt(4)
	s_barrier
	ds_read_u16 v46, v8 offset:34816
	ds_read_u16 v47, v8 offset:34944
	ds_read_u16 v48, v8 offset:35072
	ds_read_u16 v49, v8 offset:35200
	ds_read_u16 v50, v8 offset:35328
	ds_read_u16 v51, v8 offset:35456
	ds_read_u16 v52, v8 offset:35584
	ds_read_u16 v53, v8 offset:35712
	ds_read_u16 v54, v8 offset:35840
	ds_read_u16 v55, v8 offset:35968
	ds_read_u16 v56, v8 offset:36096
	ds_read_u16 v57, v8 offset:36224
	ds_read_u16 v58, v8 offset:36352
	ds_read_u16 v59, v8 offset:36480
	ds_read_u16 v60, v8 offset:36608
	ds_read_u16 v61, v8 offset:36736
	ds_read_u16 v62, v8 offset:36864
	ds_read_u16 v63, v8 offset:36992
	ds_read_u16 v64, v8 offset:37120
	ds_read_u16 v65, v8 offset:37248
	ds_read_u16 v66, v8 offset:37376
	ds_read_u16 v67, v8 offset:37504
	ds_read_u16 v68, v8 offset:37632
	ds_read_u16 v69, v8 offset:37760
	ds_read_u16 v70, v8 offset:37888
	ds_read_u16 v71, v8 offset:38016
	ds_read_u16 v72, v8 offset:38144
	ds_read_u16 v73, v8 offset:38272
	ds_read_u16 v74, v8 offset:38400
	ds_read_u16 v75, v8 offset:38528
	ds_read_u16 v76, v8 offset:38656
	ds_read_u16 v77, v8 offset:38784
	ds_read_u16 v78, v8 offset:38912
	ds_read_u16 v79, v8 offset:39040
	ds_read_u16 v80, v8 offset:39168
	ds_read_u16 v81, v8 offset:39296
	ds_read_u16 v82, v8 offset:39424
	ds_read_u16 v83, v8 offset:39552
	ds_read_u16 v84, v8 offset:39680
	ds_read_u16 v85, v8 offset:39808
	ds_read_u16 v86, v8 offset:39936
	ds_read_u16 v87, v8 offset:40064
	ds_read_u16 v88, v8 offset:40192
	ds_read_u16 v89, v8 offset:40320
	ds_read_u16 v90, v8 offset:40448
	ds_read_u16 v91, v8 offset:40576
	ds_read_u16 v92, v8 offset:40704
	s_mov_b32 s50, 0x3d800000
	s_waitcnt lgkmcnt(0)
	v_lshlrev_b32_e32 v46, 16, v46
	v_lshlrev_b32_e32 v47, 16, v47
	v_lshlrev_b32_e32 v48, 16, v48
	v_lshlrev_b32_e32 v49, 16, v49
	v_lshlrev_b32_e32 v50, 16, v50
	v_lshlrev_b32_e32 v51, 16, v51
	v_lshlrev_b32_e32 v52, 16, v52
	v_lshlrev_b32_e32 v53, 16, v53
	v_lshlrev_b32_e32 v54, 16, v54
	v_lshlrev_b32_e32 v55, 16, v55
	v_lshlrev_b32_e32 v56, 16, v56
	v_lshlrev_b32_e32 v57, 16, v57
	v_lshlrev_b32_e32 v58, 16, v58
	v_lshlrev_b32_e32 v59, 16, v59
	v_lshlrev_b32_e32 v60, 16, v60
	v_lshlrev_b32_e32 v61, 16, v61
	v_lshlrev_b32_e32 v62, 16, v62
	v_lshlrev_b32_e32 v63, 16, v63
	v_lshlrev_b32_e32 v64, 16, v64
	v_lshlrev_b32_e32 v65, 16, v65
	v_lshlrev_b32_e32 v66, 16, v66
	v_lshlrev_b32_e32 v67, 16, v67
	v_lshlrev_b32_e32 v68, 16, v68
	v_lshlrev_b32_e32 v69, 16, v69
	v_lshlrev_b32_e32 v70, 16, v70
	v_lshlrev_b32_e32 v71, 16, v71
	v_lshlrev_b32_e32 v72, 16, v72
	v_lshlrev_b32_e32 v73, 16, v73
	v_lshlrev_b32_e32 v74, 16, v74
	v_lshlrev_b32_e32 v75, 16, v75
	v_lshlrev_b32_e32 v76, 16, v76
	v_lshlrev_b32_e32 v77, 16, v77
	v_lshlrev_b32_e32 v78, 16, v78
	v_lshlrev_b32_e32 v79, 16, v79
	v_lshlrev_b32_e32 v80, 16, v80
	v_lshlrev_b32_e32 v81, 16, v81
	v_lshlrev_b32_e32 v82, 16, v82
	v_lshlrev_b32_e32 v83, 16, v83
	v_lshlrev_b32_e32 v84, 16, v84
	v_lshlrev_b32_e32 v85, 16, v85
	v_lshlrev_b32_e32 v86, 16, v86
	v_lshlrev_b32_e32 v87, 16, v87
	v_lshlrev_b32_e32 v88, 16, v88
	v_lshlrev_b32_e32 v89, 16, v89
	v_lshlrev_b32_e32 v90, 16, v90
	v_lshlrev_b32_e32 v91, 16, v91
	v_lshlrev_b32_e32 v92, 16, v92
	s_cmp_eq_u32 s42, 1
	s_cbranch_scc0 .Lpool_nz3
	v_mov_b32_e32 v60, 0
	v_mov_b32_e32 v59, 0
	v_mov_b32_e32 v58, 0
	v_mov_b32_e32 v57, 0
	v_mov_b32_e32 v56, 0
	v_mov_b32_e32 v55, 0
	v_mov_b32_e32 v54, 0
	v_mov_b32_e32 v53, 0
	v_mov_b32_e32 v52, 0
	v_mov_b32_e32 v51, 0
	v_mov_b32_e32 v50, 0
	v_mov_b32_e32 v49, 0
	v_mov_b32_e32 v48, 0
	v_mov_b32_e32 v47, 0
	v_mov_b32_e32 v46, 0
.Lpool_nz3:
	v_add_f32_e32 v93, v61, v60
	v_add_f32_e32 v93, v93, v59
	v_add_f32_e32 v93, v93, v58
	v_add_f32_e32 v93, v93, v57
	v_add_f32_e32 v93, v93, v56
	v_add_f32_e32 v93, v93, v55
	v_add_f32_e32 v93, v93, v54
	v_add_f32_e32 v93, v93, v53
	v_add_f32_e32 v93, v93, v52
	v_add_f32_e32 v93, v93, v51
	v_add_f32_e32 v93, v93, v50
	v_add_f32_e32 v93, v93, v49
	v_add_f32_e32 v93, v93, v48
	v_add_f32_e32 v93, v93, v47
	v_add_f32_e32 v93, v93, v46
	s_cmp_eq_u32 s42, 1
	s_cselect_b32 s51, 0x3f800000, s50
	v_fma_f32 v2, v93, s51, -v61
	v_add_f32_e32 v93, v93, v62
	v_sub_f32_e32 v93, v93, v46
	s_cmp_eq_u32 s42, 1
	s_cselect_b32 s51, 0x3f000000, s50
	v_fma_f32 v3, v93, s51, -v62
	v_cvt_pk_bf16_f32 v2, v2, v3
	ds_write_b16 v9, v2 offset:0
	ds_write_b16_d16_hi v9, v2 offset:144
	v_add_f32_e32 v93, v93, v63
	v_sub_f32_e32 v93, v93, v47
	s_cmp_eq_u32 s42, 1
	s_cselect_b32 s51, 0x3eaaaaab, s50
	v_fma_f32 v4, v93, s51, -v63
	v_add_f32_e32 v93, v93, v64
	v_sub_f32_e32 v93, v93, v48
	s_cmp_eq_u32 s42, 1
	s_cselect_b32 s51, 0x3e800000, s50
	v_fma_f32 v5, v93, s51, -v64
	v_cvt_pk_bf16_f32 v4, v4, v5
	ds_write_b16 v9, v4 offset:288
	ds_write_b16_d16_hi v9, v4 offset:432
	v_add_f32_e32 v93, v93, v65
	v_sub_f32_e32 v93, v93, v49
	s_cmp_eq_u32 s42, 1
	s_cselect_b32 s51, 0x3e4ccccd, s50
	v_fma_f32 v2, v93, s51, -v65
	v_add_f32_e32 v93, v93, v66
	v_sub_f32_e32 v93, v93, v50
	s_cmp_eq_u32 s42, 1
	s_cselect_b32 s51, 0x3e2aaaab, s50
	v_fma_f32 v3, v93, s51, -v66
	v_cvt_pk_bf16_f32 v2, v2, v3
	ds_write_b16 v9, v2 offset:576
	ds_write_b16_d16_hi v9, v2 offset:720
	v_add_f32_e32 v93, v93, v67
	v_sub_f32_e32 v93, v93, v51
	s_cmp_eq_u32 s42, 1
	s_cselect_b32 s51, 0x3e124925, s50
	v_fma_f32 v4, v93, s51, -v67
	v_add_f32_e32 v93, v93, v68
	v_sub_f32_e32 v93, v93, v52
	s_cmp_eq_u32 s42, 1
	s_cselect_b32 s51, 0x3e000000, s50
	v_fma_f32 v5, v93, s51, -v68
	v_cvt_pk_bf16_f32 v4, v4, v5
	ds_write_b16 v9, v4 offset:864
	ds_write_b16_d16_hi v9, v4 offset:1008
	v_add_f32_e32 v93, v93, v69
	v_sub_f32_e32 v93, v93, v53
	s_cmp_eq_u32 s42, 1
	s_cselect_b32 s51, 0x3de38e39, s50
	v_fma_f32 v2, v93, s51, -v69
	v_add_f32_e32 v93, v93, v70
	v_sub_f32_e32 v93, v93, v54
	s_cmp_eq_u32 s42, 1
	s_cselect_b32 s51, 0x3dcccccd, s50
	v_fma_f32 v3, v93, s51, -v70
	v_cvt_pk_bf16_f32 v2, v2, v3
	ds_write_b16 v9, v2 offset:1152
	ds_write_b16_d16_hi v9, v2 offset:1296
	v_add_f32_e32 v93, v93, v71
	v_sub_f32_e32 v93, v93, v55
	s_cmp_eq_u32 s42, 1
	s_cselect_b32 s51, 0x3dba2e8c, s50
	v_fma_f32 v4, v93, s51, -v71
	v_add_f32_e32 v93, v93, v72
	v_sub_f32_e32 v93, v93, v56
	s_cmp_eq_u32 s42, 1
	s_cselect_b32 s51, 0x3daaaaab, s50
	v_fma_f32 v5, v93, s51, -v72
	v_cvt_pk_bf16_f32 v4, v4, v5
	ds_write_b16 v9, v4 offset:1440
	ds_write_b16_d16_hi v9, v4 offset:1584
	v_add_f32_e32 v93, v93, v73
	v_sub_f32_e32 v93, v93, v57
	s_cmp_eq_u32 s42, 1
	s_cselect_b32 s51, 0x3d9d89d9, s50
	v_fma_f32 v2, v93, s51, -v73
	v_add_f32_e32 v93, v93, v74
	v_sub_f32_e32 v93, v93, v58
	s_cmp_eq_u32 s42, 1
	s_cselect_b32 s51, 0x3d924925, s50
	v_fma_f32 v3, v93, s51, -v74
	v_cvt_pk_bf16_f32 v2, v2, v3
	ds_write_b16 v9, v2 offset:1728
	ds_write_b16_d16_hi v9, v2 offset:1872
	v_add_f32_e32 v93, v93, v75
	v_sub_f32_e32 v93, v93, v59
	s_cmp_eq_u32 s42, 1
	s_cselect_b32 s51, 0x3d888889, s50
	v_fma_f32 v4, v93, s51, -v75
	v_add_f32_e32 v93, v93, v76
	v_sub_f32_e32 v93, v93, v60
	v_fma_f32 v5, v93, s50, -v76
	v_cvt_pk_bf16_f32 v4, v4, v5
	ds_write_b16 v9, v4 offset:2016
	ds_write_b16_d16_hi v9, v4 offset:2160
	v_add_f32_e32 v93, v93, v77
	v_sub_f32_e32 v93, v93, v61
	v_fma_f32 v2, v93, s50, -v77
	v_add_f32_e32 v93, v93, v78
	v_sub_f32_e32 v93, v93, v62
	v_fma_f32 v3, v93, s50, -v78
	v_cvt_pk_bf16_f32 v2, v2, v3
	ds_write_b16 v9, v2 offset:2304
	ds_write_b16_d16_hi v9, v2 offset:2448
	v_add_f32_e32 v93, v93, v79
	v_sub_f32_e32 v93, v93, v63
	v_fma_f32 v4, v93, s50, -v79
	v_add_f32_e32 v93, v93, v80
	v_sub_f32_e32 v93, v93, v64
	v_fma_f32 v5, v93, s50, -v80
	v_cvt_pk_bf16_f32 v4, v4, v5
	ds_write_b16 v9, v4 offset:2592
	ds_write_b16_d16_hi v9, v4 offset:2736
	v_add_f32_e32 v93, v93, v81
	v_sub_f32_e32 v93, v93, v65
	v_fma_f32 v2, v93, s50, -v81
	v_add_f32_e32 v93, v93, v82
	v_sub_f32_e32 v93, v93, v66
	v_fma_f32 v3, v93, s50, -v82
	v_cvt_pk_bf16_f32 v2, v2, v3
	ds_write_b16 v9, v2 offset:2880
	ds_write_b16_d16_hi v9, v2 offset:3024
	v_add_f32_e32 v93, v93, v83
	v_sub_f32_e32 v93, v93, v67
	v_fma_f32 v4, v93, s50, -v83
	v_add_f32_e32 v93, v93, v84
	v_sub_f32_e32 v93, v93, v68
	v_fma_f32 v5, v93, s50, -v84
	v_cvt_pk_bf16_f32 v4, v4, v5
	ds_write_b16 v9, v4 offset:3168
	ds_write_b16_d16_hi v9, v4 offset:3312
	v_add_f32_e32 v93, v93, v85
	v_sub_f32_e32 v93, v93, v69
	v_fma_f32 v2, v93, s50, -v85
	v_add_f32_e32 v93, v93, v86
	v_sub_f32_e32 v93, v93, v70
	v_fma_f32 v3, v93, s50, -v86
	v_cvt_pk_bf16_f32 v2, v2, v3
	ds_write_b16 v9, v2 offset:3456
	ds_write_b16_d16_hi v9, v2 offset:3600
	v_add_f32_e32 v93, v93, v87
	v_sub_f32_e32 v93, v93, v71
	v_fma_f32 v4, v93, s50, -v87
	v_add_f32_e32 v93, v93, v88
	v_sub_f32_e32 v93, v93, v72
	v_fma_f32 v5, v93, s50, -v88
	v_cvt_pk_bf16_f32 v4, v4, v5
	ds_write_b16 v9, v4 offset:3744
	ds_write_b16_d16_hi v9, v4 offset:3888
	v_add_f32_e32 v93, v93, v89
	v_sub_f32_e32 v93, v93, v73
	v_fma_f32 v2, v93, s50, -v89
	v_add_f32_e32 v93, v93, v90
	v_sub_f32_e32 v93, v93, v74
	v_fma_f32 v3, v93, s50, -v90
	v_cvt_pk_bf16_f32 v2, v2, v3
	ds_write_b16 v9, v2 offset:4032
	ds_write_b16_d16_hi v9, v2 offset:4176
	v_add_f32_e32 v93, v93, v91
	v_sub_f32_e32 v93, v93, v75
	v_fma_f32 v4, v93, s50, -v91
	v_add_f32_e32 v93, v93, v92
	v_sub_f32_e32 v93, v93, v76
	v_fma_f32 v5, v93, s50, -v92
	v_cvt_pk_bf16_f32 v4, v4, v5
	ds_write_b16 v9, v4 offset:4320
	ds_write_b16_d16_hi v9, v4 offset:4464
	v_and_b32_e32 v2, 31, v0
	v_lshrrev_b32_e32 v3, 5, v0
	v_bfe_u32 v4, v0, 1, 3
	v_xor_b32_e32 v3, v3, v4
	v_lshlrev_b32_e32 v2, 7, v2
	v_add_u32_e32 v2, 0x1c000, v2
	v_lshl_add_u32 v5, v3, 4, v2
	v_xor_b32_e32 v4, 2, v3
	v_lshl_add_u32 v4, v4, 4, v2
	v_xor_b32_e32 v88, 4, v3
	v_xor_b32_e32 v3, 6, v3
	v_lshl_add_u32 v3, v3, 4, v2
	v_lshl_add_u32 v2, v88, 4, v2
	s_waitcnt lgkmcnt(0)
	ds_read_b128 v[28:31], v5 offset:0
	ds_read_b128 v[32:35], v5 offset:4096
	ds_read_b128 v[78:81], v44 offset:0
	ds_read_b128 v[82:85], v44 offset:32
	ds_read_b128 v[86:89], v44 offset:64
	ds_read_b128 v[90:93], v44 offset:96
	ds_read_b128 v[36:39], v4 offset:0
	ds_read_b128 v[40:43], v4 offset:4096
	s_waitcnt lgkmcnt(0)
	v_mfma_f32_32x32x16_bf16 v[46:61], v[28:31], v[78:81], 0
	v_mfma_f32_32x32x16_bf16 v[62:77], v[32:35], v[78:81], 0
	ds_read_b128 v[28:31], v2 offset:0
	ds_read_b128 v[32:35], v2 offset:4096
	v_mfma_f32_32x32x16_bf16 v[46:61], v[36:39], v[82:85], v[46:61]
	v_mfma_f32_32x32x16_bf16 v[62:77], v[40:43], v[82:85], v[62:77]
	ds_read_b128 v[36:39], v3 offset:0
	ds_read_b128 v[40:43], v3 offset:4096
	s_waitcnt lgkmcnt(2)
	v_mfma_f32_32x32x16_bf16 v[46:61], v[28:31], v[86:89], v[46:61]
	v_mfma_f32_32x32x16_bf16 v[62:77], v[32:35], v[86:89], v[62:77]
	s_waitcnt lgkmcnt(0)
	v_mfma_f32_32x32x16_bf16 v[46:61], v[36:39], v[90:93], v[46:61]
	v_mfma_f32_32x32x16_bf16 v[62:77], v[40:43], v[90:93], v[62:77]
	v_lshl_add_u64 v[4:5], s[52:53], 0, v[10:11]
	v_lshl_add_u64 v[98:99], s[52:53], 0, v[96:97]
	s_nop 14
	s_waitcnt vmcnt(0)
	v_permlane32_swap_b32 v12, v14
	v_permlane32_swap_b32 v13, v15
	v_permlane32_swap_b32 v16, v18
	v_permlane32_swap_b32 v17, v19
	v_permlane32_swap_b32 v20, v22
	v_permlane32_swap_b32 v21, v23
	v_permlane32_swap_b32 v24, v26
	v_permlane32_swap_b32 v25, v27
	s_mov_b32 s56, 0xbfb8aa3b
	s_mov_b32 s57, 0xbfb8aa3b
	s_mov_b32 s54, 1.0
	s_mov_b32 s55, 1.0
	v_lshlrev_b32_e32 v78, 16, v12
	v_and_b32_e32 v79, 0xffff0000, v12
	v_lshlrev_b32_e32 v80, 16, v13
	v_and_b32_e32 v81, 0xffff0000, v13
	v_lshlrev_b32_e32 v82, 16, v14
	v_and_b32_e32 v83, 0xffff0000, v14
	v_lshlrev_b32_e32 v84, 16, v15
	v_and_b32_e32 v85, 0xffff0000, v15
	v_lshlrev_b32_e32 v86, 16, v16
	v_and_b32_e32 v87, 0xffff0000, v16
	v_lshlrev_b32_e32 v88, 16, v17
	v_and_b32_e32 v89, 0xffff0000, v17
	v_lshlrev_b32_e32 v90, 16, v18
	v_and_b32_e32 v91, 0xffff0000, v18
	v_lshlrev_b32_e32 v92, 16, v19
	v_and_b32_e32 v93, 0xffff0000, v19
	v_pk_mul_f32 v[28:29], v[78:79], s[56:57]
	v_pk_mul_f32 v[30:31], v[80:81], s[56:57]
	v_pk_mul_f32 v[32:33], v[82:83], s[56:57]
	v_pk_mul_f32 v[34:35], v[84:85], s[56:57]
	v_pk_mul_f32 v[36:37], v[86:87], s[56:57]
	v_pk_mul_f32 v[38:39], v[88:89], s[56:57]
	v_pk_mul_f32 v[40:41], v[90:91], s[56:57]
	v_pk_mul_f32 v[42:43], v[92:93], s[56:57]
	v_exp_f32_e32 v28, v28
	v_exp_f32_e32 v29, v29
	v_exp_f32_e32 v30, v30
	v_exp_f32_e32 v31, v31
	v_exp_f32_e32 v32, v32
	v_exp_f32_e32 v33, v33
	v_exp_f32_e32 v34, v34
	v_exp_f32_e32 v35, v35
	v_exp_f32_e32 v36, v36
	v_exp_f32_e32 v37, v37
	v_exp_f32_e32 v38, v38
	v_exp_f32_e32 v39, v39
	v_exp_f32_e32 v40, v40
	v_exp_f32_e32 v41, v41
	v_exp_f32_e32 v42, v42
	v_exp_f32_e32 v43, v43
	v_pk_add_f32 v[28:29], v[28:29], s[54:55]
	v_pk_add_f32 v[30:31], v[30:31], s[54:55]
	v_pk_add_f32 v[32:33], v[32:33], s[54:55]
	v_pk_add_f32 v[34:35], v[34:35], s[54:55]
	v_pk_add_f32 v[36:37], v[36:37], s[54:55]
	v_pk_add_f32 v[38:39], v[38:39], s[54:55]
	v_pk_add_f32 v[40:41], v[40:41], s[54:55]
	v_pk_add_f32 v[42:43], v[42:43], s[54:55]
	v_rcp_f32_e32 v28, v28
	v_rcp_f32_e32 v29, v29
	v_rcp_f32_e32 v30, v30
	v_rcp_f32_e32 v31, v31
	v_rcp_f32_e32 v32, v32
	v_rcp_f32_e32 v33, v33
	v_rcp_f32_e32 v34, v34
	v_rcp_f32_e32 v35, v35
	v_rcp_f32_e32 v36, v36
	v_rcp_f32_e32 v37, v37
	v_rcp_f32_e32 v38, v38
	v_rcp_f32_e32 v39, v39
	v_rcp_f32_e32 v40, v40
	v_rcp_f32_e32 v41, v41
	v_rcp_f32_e32 v42, v42
	v_rcp_f32_e32 v43, v43
	v_pk_mul_f32 v[28:29], v[78:79], v[28:29]
	v_pk_mul_f32 v[30:31], v[80:81], v[30:31]
	v_pk_mul_f32 v[32:33], v[82:83], v[32:33]
	v_pk_mul_f32 v[34:35], v[84:85], v[34:35]
	v_pk_mul_f32 v[36:37], v[86:87], v[36:37]
	v_pk_mul_f32 v[38:39], v[88:89], v[38:39]
	v_pk_mul_f32 v[40:41], v[90:91], v[40:41]
	v_pk_mul_f32 v[42:43], v[92:93], v[42:43]
	v_pk_mul_f32 v[28:29], v[46:47], v[28:29]
	v_pk_mul_f32 v[30:31], v[48:49], v[30:31]
	v_pk_mul_f32 v[32:33], v[50:51], v[32:33]
	v_pk_mul_f32 v[34:35], v[52:53], v[34:35]
	v_pk_mul_f32 v[36:37], v[54:55], v[36:37]
	v_pk_mul_f32 v[38:39], v[56:57], v[38:39]
	v_pk_mul_f32 v[40:41], v[58:59], v[40:41]
	v_pk_mul_f32 v[42:43], v[60:61], v[42:43]
	v_cvt_pk_bf16_f32 v78, v28, v29
	v_cvt_pk_bf16_f32 v79, v30, v31
	v_cvt_pk_bf16_f32 v80, v32, v33
	v_cvt_pk_bf16_f32 v81, v34, v35
	v_cvt_pk_bf16_f32 v82, v36, v37
	v_cvt_pk_bf16_f32 v83, v38, v39
	v_cvt_pk_bf16_f32 v84, v40, v41
	v_cvt_pk_bf16_f32 v85, v42, v43
	s_nop 1
	v_permlane32_swap_b32 v78, v80
	v_permlane32_swap_b32 v79, v81
	v_permlane32_swap_b32 v82, v84
	v_permlane32_swap_b32 v83, v85
	global_store_dwordx4 v[98:99], v[78:81], off offset:384
	global_store_dwordx4 v[98:99], v[82:85], off offset:416
	s_nop 1
	v_lshlrev_b32_e32 v78, 16, v20
	v_and_b32_e32 v79, 0xffff0000, v20
	v_lshlrev_b32_e32 v80, 16, v21
	v_and_b32_e32 v81, 0xffff0000, v21
	v_lshlrev_b32_e32 v82, 16, v22
	v_and_b32_e32 v83, 0xffff0000, v22
	v_lshlrev_b32_e32 v84, 16, v23
	v_and_b32_e32 v85, 0xffff0000, v23
	v_lshlrev_b32_e32 v86, 16, v24
	v_and_b32_e32 v87, 0xffff0000, v24
	v_lshlrev_b32_e32 v88, 16, v25
	v_and_b32_e32 v89, 0xffff0000, v25
	v_lshlrev_b32_e32 v90, 16, v26
	v_and_b32_e32 v91, 0xffff0000, v26
	v_lshlrev_b32_e32 v92, 16, v27
	v_and_b32_e32 v93, 0xffff0000, v27
	v_pk_mul_f32 v[28:29], v[78:79], s[56:57]
	v_pk_mul_f32 v[30:31], v[80:81], s[56:57]
	v_pk_mul_f32 v[32:33], v[82:83], s[56:57]
	v_pk_mul_f32 v[34:35], v[84:85], s[56:57]
	v_pk_mul_f32 v[36:37], v[86:87], s[56:57]
	v_pk_mul_f32 v[38:39], v[88:89], s[56:57]
	v_pk_mul_f32 v[40:41], v[90:91], s[56:57]
	v_pk_mul_f32 v[42:43], v[92:93], s[56:57]
	v_exp_f32_e32 v28, v28
	v_exp_f32_e32 v29, v29
	v_exp_f32_e32 v30, v30
	v_exp_f32_e32 v31, v31
	v_exp_f32_e32 v32, v32
	v_exp_f32_e32 v33, v33
	v_exp_f32_e32 v34, v34
	v_exp_f32_e32 v35, v35
	v_exp_f32_e32 v36, v36
	v_exp_f32_e32 v37, v37
	v_exp_f32_e32 v38, v38
	v_exp_f32_e32 v39, v39
	v_exp_f32_e32 v40, v40
	v_exp_f32_e32 v41, v41
	v_exp_f32_e32 v42, v42
	v_exp_f32_e32 v43, v43
	v_pk_add_f32 v[28:29], v[28:29], s[54:55]
	v_pk_add_f32 v[30:31], v[30:31], s[54:55]
	v_pk_add_f32 v[32:33], v[32:33], s[54:55]
	v_pk_add_f32 v[34:35], v[34:35], s[54:55]
	v_pk_add_f32 v[36:37], v[36:37], s[54:55]
	v_pk_add_f32 v[38:39], v[38:39], s[54:55]
	v_pk_add_f32 v[40:41], v[40:41], s[54:55]
	v_pk_add_f32 v[42:43], v[42:43], s[54:55]
	v_rcp_f32_e32 v28, v28
	v_rcp_f32_e32 v29, v29
	v_rcp_f32_e32 v30, v30
	v_rcp_f32_e32 v31, v31
	v_rcp_f32_e32 v32, v32
	v_rcp_f32_e32 v33, v33
	v_rcp_f32_e32 v34, v34
	v_rcp_f32_e32 v35, v35
	v_rcp_f32_e32 v36, v36
	v_rcp_f32_e32 v37, v37
	v_rcp_f32_e32 v38, v38
	v_rcp_f32_e32 v39, v39
	v_rcp_f32_e32 v40, v40
	v_rcp_f32_e32 v41, v41
	v_rcp_f32_e32 v42, v42
	v_rcp_f32_e32 v43, v43
	v_pk_mul_f32 v[28:29], v[78:79], v[28:29]
	v_pk_mul_f32 v[30:31], v[80:81], v[30:31]
	v_pk_mul_f32 v[32:33], v[82:83], v[32:33]
	v_pk_mul_f32 v[34:35], v[84:85], v[34:35]
	v_pk_mul_f32 v[36:37], v[86:87], v[36:37]
	v_pk_mul_f32 v[38:39], v[88:89], v[38:39]
	v_pk_mul_f32 v[40:41], v[90:91], v[40:41]
	v_pk_mul_f32 v[42:43], v[92:93], v[42:43]
	v_pk_mul_f32 v[28:29], v[62:63], v[28:29]
	v_pk_mul_f32 v[30:31], v[64:65], v[30:31]
	v_pk_mul_f32 v[32:33], v[66:67], v[32:33]
	v_pk_mul_f32 v[34:35], v[68:69], v[34:35]
	v_pk_mul_f32 v[36:37], v[70:71], v[36:37]
	v_pk_mul_f32 v[38:39], v[72:73], v[38:39]
	v_pk_mul_f32 v[40:41], v[74:75], v[40:41]
	v_pk_mul_f32 v[42:43], v[76:77], v[42:43]
	v_cvt_pk_bf16_f32 v78, v28, v29
	v_cvt_pk_bf16_f32 v79, v30, v31
	v_cvt_pk_bf16_f32 v80, v32, v33
	v_cvt_pk_bf16_f32 v81, v34, v35
	v_cvt_pk_bf16_f32 v82, v36, v37
	v_cvt_pk_bf16_f32 v83, v38, v39
	v_cvt_pk_bf16_f32 v84, v40, v41
	v_cvt_pk_bf16_f32 v85, v42, v43
	s_nop 1
	v_permlane32_swap_b32 v78, v80
	v_permlane32_swap_b32 v79, v81
	v_permlane32_swap_b32 v82, v84
	v_permlane32_swap_b32 v83, v85
	global_store_dwordx4 v[98:99], v[78:81], off offset:448
	global_store_dwordx4 v[98:99], v[82:85], off offset:480
	s_waitcnt vmcnt(0)
	s_mov_b32 m0, s59
	v_readlane_b32 s38, v250, 39
	v_readlane_b32 s39, v250, 40
	s_barrier

.LBB0_209:
	s_or_b64 exec, exec, s[48:49]
	v_lshlrev_b32_e32 v0, 10, v129
	v_and_b32_e32 v0, 0x3000, v0
	v_add_u32_e32 v34, v120, v0
	v_ashrrev_i32_e32 v35, 31, v34
	v_lshlrev_b64 v[34:35], 11, v[34:35]
	v_lshlrev_b32_e32 v0, 7, v129
	v_lshl_add_u64 v[34:35], s[70:71], 0, v[34:35]
	v_and_b32_e32 v0, 0x180, v0
	v_lshl_add_u64 v[34:35], v[34:35], 0, v[0:1]
	v_lshlrev_b32_e32 v0, 3, v115
	v_lshl_add_u64 v[36:37], v[34:35], 0, v[0:1]
	s_mov_b64 s[38:39], 0x95c8600
	v_lshl_add_u64 v[34:35], v[36:37], 0, s[38:39]
	v_add_co_u32_e32 v36, vcc, 0x95c8000, v36
	s_nop 1
	v_addc_co_u32_e32 v37, vcc, 0, v37, vcc
	v_and_b32_e32 v96, 32, v216
	v_lshrrev_b32_e32 v96, 2, v96
	v_mov_b32_e32 v97, 0
	v_lshl_add_u64 v[98:99], v[34:35], 0, v[96:97]
	global_load_dwordx4 v[44:47], v[98:99], off
	global_load_dwordx4 v[48:51], v[98:99], off offset:32
	global_load_dwordx4 v[52:55], v[98:99], off offset:64
	global_load_dwordx4 v[56:59], v[98:99], off offset:96
	s_mov_b32 s38, 0xbfb8aa3b
	s_mov_b32 s39, 0xbfb8aa3b
	s_mov_b32 s48, 1.0
	s_mov_b32 s49, 1.0
	s_waitcnt vmcnt(0)
	v_permlane32_swap_b32 v44, v46
	v_permlane32_swap_b32 v45, v47
	v_permlane32_swap_b32 v48, v50
	v_permlane32_swap_b32 v49, v51
	v_permlane32_swap_b32 v52, v54
	v_permlane32_swap_b32 v53, v55
	v_permlane32_swap_b32 v56, v58
	v_permlane32_swap_b32 v57, v59
	v_lshlrev_b32_e32 v64, 16, v44
	v_and_b32_e32 v65, 0xffff0000, v44
	v_lshlrev_b32_e32 v66, 16, v45
	v_and_b32_e32 v67, 0xffff0000, v45
	v_lshlrev_b32_e32 v68, 16, v46
	v_and_b32_e32 v69, 0xffff0000, v46
	v_lshlrev_b32_e32 v70, 16, v47
	v_and_b32_e32 v71, 0xffff0000, v47
	v_lshlrev_b32_e32 v72, 16, v48
	v_and_b32_e32 v73, 0xffff0000, v48
	v_lshlrev_b32_e32 v74, 16, v49
	v_and_b32_e32 v75, 0xffff0000, v49
	v_lshlrev_b32_e32 v76, 16, v50
	v_and_b32_e32 v77, 0xffff0000, v50
	v_lshlrev_b32_e32 v78, 16, v51
	v_and_b32_e32 v79, 0xffff0000, v51
	v_pk_mul_f32 v[80:81], v[64:65], s[38:39]
	v_pk_mul_f32 v[82:83], v[66:67], s[38:39]
	v_pk_mul_f32 v[84:85], v[68:69], s[38:39]
	v_pk_mul_f32 v[86:87], v[70:71], s[38:39]
	v_pk_mul_f32 v[88:89], v[72:73], s[38:39]
	v_pk_mul_f32 v[90:91], v[74:75], s[38:39]
	v_pk_mul_f32 v[92:93], v[76:77], s[38:39]
	v_pk_mul_f32 v[94:95], v[78:79], s[38:39]
	v_exp_f32_e32 v80, v80
	v_exp_f32_e32 v81, v81
	v_exp_f32_e32 v82, v82
	v_exp_f32_e32 v83, v83
	v_exp_f32_e32 v84, v84
	v_exp_f32_e32 v85, v85
	v_exp_f32_e32 v86, v86
	v_exp_f32_e32 v87, v87
	v_exp_f32_e32 v88, v88
	v_exp_f32_e32 v89, v89
	v_exp_f32_e32 v90, v90
	v_exp_f32_e32 v91, v91
	v_exp_f32_e32 v92, v92
	v_exp_f32_e32 v93, v93
	v_exp_f32_e32 v94, v94
	v_exp_f32_e32 v95, v95
	v_pk_add_f32 v[80:81], v[80:81], s[48:49]
	v_pk_add_f32 v[82:83], v[82:83], s[48:49]
	v_pk_add_f32 v[84:85], v[84:85], s[48:49]
	v_pk_add_f32 v[86:87], v[86:87], s[48:49]
	v_pk_add_f32 v[88:89], v[88:89], s[48:49]
	v_pk_add_f32 v[90:91], v[90:91], s[48:49]
	v_pk_add_f32 v[92:93], v[92:93], s[48:49]
	v_pk_add_f32 v[94:95], v[94:95], s[48:49]
	v_rcp_f32_e32 v80, v80
	v_rcp_f32_e32 v81, v81
	v_rcp_f32_e32 v82, v82
	v_rcp_f32_e32 v83, v83
	v_rcp_f32_e32 v84, v84
	v_rcp_f32_e32 v85, v85
	v_rcp_f32_e32 v86, v86
	v_rcp_f32_e32 v87, v87
	v_rcp_f32_e32 v88, v88
	v_rcp_f32_e32 v89, v89
	v_rcp_f32_e32 v90, v90
	v_rcp_f32_e32 v91, v91
	v_rcp_f32_e32 v92, v92
	v_rcp_f32_e32 v93, v93
	v_rcp_f32_e32 v94, v94
	v_rcp_f32_e32 v95, v95
	v_pk_mul_f32 v[80:81], v[80:81], v[64:65]
	v_pk_mul_f32 v[82:83], v[82:83], v[66:67]
	v_pk_mul_f32 v[84:85], v[84:85], v[68:69]
	v_pk_mul_f32 v[86:87], v[86:87], v[70:71]
	v_pk_mul_f32 v[88:89], v[88:89], v[72:73]
	v_pk_mul_f32 v[90:91], v[90:91], v[74:75]
	v_pk_mul_f32 v[92:93], v[92:93], v[76:77]
	v_pk_mul_f32 v[94:95], v[94:95], v[78:79]
	v_pk_mul_f32 v[80:81], v[2:3], v[80:81]
	v_pk_mul_f32 v[82:83], v[4:5], v[82:83]
	v_pk_mul_f32 v[84:85], v[6:7], v[84:85]
	v_pk_mul_f32 v[86:87], v[8:9], v[86:87]
	v_pk_mul_f32 v[88:89], v[10:11], v[88:89]
	v_pk_mul_f32 v[90:91], v[12:13], v[90:91]
	v_pk_mul_f32 v[92:93], v[14:15], v[92:93]
	v_pk_mul_f32 v[94:95], v[16:17], v[94:95]
	v_cvt_pk_bf16_f32 v64, v80, v81
	v_cvt_pk_bf16_f32 v65, v82, v83
	v_cvt_pk_bf16_f32 v66, v84, v85
	v_cvt_pk_bf16_f32 v67, v86, v87
	v_cvt_pk_bf16_f32 v68, v88, v89
	v_cvt_pk_bf16_f32 v69, v90, v91
	v_cvt_pk_bf16_f32 v70, v92, v93
	v_cvt_pk_bf16_f32 v71, v94, v95
	s_nop 1
	v_permlane32_swap_b32 v64, v66
	v_permlane32_swap_b32 v65, v67
	v_permlane32_swap_b32 v68, v70
	v_permlane32_swap_b32 v69, v71
	global_store_dwordx4 v[98:99], v[64:67], off
	global_store_dwordx4 v[98:99], v[68:71], off offset:32
	s_nop 1
	v_lshlrev_b32_e32 v64, 16, v52
	v_and_b32_e32 v65, 0xffff0000, v52
	v_lshlrev_b32_e32 v66, 16, v53
	v_and_b32_e32 v67, 0xffff0000, v53
	v_lshlrev_b32_e32 v68, 16, v54
	v_and_b32_e32 v69, 0xffff0000, v54
	v_lshlrev_b32_e32 v70, 16, v55
	v_and_b32_e32 v71, 0xffff0000, v55
	v_lshlrev_b32_e32 v72, 16, v56
	v_and_b32_e32 v73, 0xffff0000, v56
	v_lshlrev_b32_e32 v74, 16, v57
	v_and_b32_e32 v75, 0xffff0000, v57
	v_lshlrev_b32_e32 v76, 16, v58
	v_and_b32_e32 v77, 0xffff0000, v58
	v_lshlrev_b32_e32 v78, 16, v59
	v_and_b32_e32 v79, 0xffff0000, v59
	v_pk_mul_f32 v[80:81], v[64:65], s[38:39]
	v_pk_mul_f32 v[82:83], v[66:67], s[38:39]
	v_pk_mul_f32 v[84:85], v[68:69], s[38:39]
	v_pk_mul_f32 v[86:87], v[70:71], s[38:39]
	v_pk_mul_f32 v[88:89], v[72:73], s[38:39]
	v_pk_mul_f32 v[90:91], v[74:75], s[38:39]
	v_pk_mul_f32 v[92:93], v[76:77], s[38:39]
	v_pk_mul_f32 v[94:95], v[78:79], s[38:39]
	v_exp_f32_e32 v80, v80
	v_exp_f32_e32 v81, v81
	v_exp_f32_e32 v82, v82
	v_exp_f32_e32 v83, v83
	v_exp_f32_e32 v84, v84
	v_exp_f32_e32 v85, v85
	v_exp_f32_e32 v86, v86
	v_exp_f32_e32 v87, v87
	v_exp_f32_e32 v88, v88
	v_exp_f32_e32 v89, v89
	v_exp_f32_e32 v90, v90
	v_exp_f32_e32 v91, v91
	v_exp_f32_e32 v92, v92
	v_exp_f32_e32 v93, v93
	v_exp_f32_e32 v94, v94
	v_exp_f32_e32 v95, v95
	v_pk_add_f32 v[80:81], v[80:81], s[48:49]
	v_pk_add_f32 v[82:83], v[82:83], s[48:49]
	v_pk_add_f32 v[84:85], v[84:85], s[48:49]
	v_pk_add_f32 v[86:87], v[86:87], s[48:49]
	v_pk_add_f32 v[88:89], v[88:89], s[48:49]
	v_pk_add_f32 v[90:91], v[90:91], s[48:49]
	v_pk_add_f32 v[92:93], v[92:93], s[48:49]
	v_pk_add_f32 v[94:95], v[94:95], s[48:49]
	v_rcp_f32_e32 v80, v80
	v_rcp_f32_e32 v81, v81
	v_rcp_f32_e32 v82, v82
	v_rcp_f32_e32 v83, v83
	v_rcp_f32_e32 v84, v84
	v_rcp_f32_e32 v85, v85
	v_rcp_f32_e32 v86, v86
	v_rcp_f32_e32 v87, v87
	v_rcp_f32_e32 v88, v88
	v_rcp_f32_e32 v89, v89
	v_rcp_f32_e32 v90, v90
	v_rcp_f32_e32 v91, v91
	v_rcp_f32_e32 v92, v92
	v_rcp_f32_e32 v93, v93
	v_rcp_f32_e32 v94, v94
	v_rcp_f32_e32 v95, v95
	v_pk_mul_f32 v[80:81], v[80:81], v[64:65]
	v_pk_mul_f32 v[82:83], v[82:83], v[66:67]
	v_pk_mul_f32 v[84:85], v[84:85], v[68:69]
	v_pk_mul_f32 v[86:87], v[86:87], v[70:71]
	v_pk_mul_f32 v[88:89], v[88:89], v[72:73]
	v_pk_mul_f32 v[90:91], v[90:91], v[74:75]
	v_pk_mul_f32 v[92:93], v[92:93], v[76:77]
	v_pk_mul_f32 v[94:95], v[94:95], v[78:79]
	v_pk_mul_f32 v[80:81], v[18:19], v[80:81]
	v_pk_mul_f32 v[82:83], v[20:21], v[82:83]
	v_pk_mul_f32 v[84:85], v[22:23], v[84:85]
	v_pk_mul_f32 v[86:87], v[24:25], v[86:87]
	v_pk_mul_f32 v[88:89], v[26:27], v[88:89]
	v_pk_mul_f32 v[90:91], v[28:29], v[90:91]
	v_pk_mul_f32 v[92:93], v[30:31], v[92:93]
	v_pk_mul_f32 v[94:95], v[32:33], v[94:95]
	v_cvt_pk_bf16_f32 v64, v80, v81
	v_cvt_pk_bf16_f32 v65, v82, v83
	v_cvt_pk_bf16_f32 v66, v84, v85
	v_cvt_pk_bf16_f32 v67, v86, v87
	v_cvt_pk_bf16_f32 v68, v88, v89
	v_cvt_pk_bf16_f32 v69, v90, v91
	v_cvt_pk_bf16_f32 v70, v92, v93
	v_cvt_pk_bf16_f32 v71, v94, v95
	s_nop 1
	v_permlane32_swap_b32 v64, v66
	v_permlane32_swap_b32 v65, v67
	v_permlane32_swap_b32 v68, v70
	v_permlane32_swap_b32 v69, v71
	global_store_dwordx4 v[98:99], v[64:67], off offset:64
	global_store_dwordx4 v[98:99], v[68:71], off offset:96
	s_waitcnt lgkmcnt(0)
	s_barrier

.LBB0_257:
	s_or_b64 exec, exec, s[42:43]
	v_xor_b32_e32 v0, 32, v216
	v_add_u32_e32 v2, 64, v113
	v_cmp_lt_i32_e32 vcc, v0, v2
	v_readlane_b32 s38, v251, 27
	v_readlane_b32 s39, v251, 28
	v_cndmask_b32_e32 v0, v216, v0, vcc
	v_lshlrev_b32_e32 v0, 2, v0
	ds_bpermute_b32 v0, v0, v148
	s_waitcnt lgkmcnt(0)
	v_add_f32_e32 v0, v148, v0
	v_rcp_f32_e32 v4, v0
	v_lshlrev_b32_e32 v0, 9, v120
	v_and_b32_e32 v0, 0x3000, v0
	v_add_u32_e32 v2, v112, v0
	v_ashrrev_i32_e32 v3, 31, v2
	v_lshlrev_b64 v[2:3], 11, v[2:3]
	v_lshlrev_b32_e32 v0, 7, v120
	v_lshl_add_u64 v[2:3], s[38:39], 0, v[2:3]
	v_and_b32_e32 v0, 0x380, v0
	v_lshl_add_u64 v[2:3], v[2:3], 0, v[0:1]
	v_lshlrev_b32_e32 v0, 3, v121
	v_lshl_add_u64 v[2:3], v[2:3], 0, v[0:1]
	v_and_b32_e32 v96, 32, v216
	v_lshrrev_b32_e32 v96, 2, v96
	v_mov_b32_e32 v97, 0
	v_lshl_add_u64 v[98:99], v[2:3], 0, v[96:97]
	global_load_dwordx4 v[192:195], v[98:99], off
	global_load_dwordx4 v[196:199], v[98:99], off offset:32
	global_load_dwordx4 v[200:203], v[98:99], off offset:64
	global_load_dwordx4 v[204:207], v[98:99], off offset:96
	s_mov_b32 s44, 0xbfb8aa3b
	s_mov_b32 s45, 0xbfb8aa3b
	s_mov_b32 s46, 1.0
	s_mov_b32 s47, 1.0
	v_pk_mul_f32 v[32:33], v[32:33], v[4:5] op_sel_hi:[1,0]
	v_pk_mul_f32 v[34:35], v[34:35], v[4:5] op_sel_hi:[1,0]
	v_pk_mul_f32 v[36:37], v[36:37], v[4:5] op_sel_hi:[1,0]
	v_pk_mul_f32 v[38:39], v[38:39], v[4:5] op_sel_hi:[1,0]
	v_pk_mul_f32 v[40:41], v[40:41], v[4:5] op_sel_hi:[1,0]
	v_pk_mul_f32 v[42:43], v[42:43], v[4:5] op_sel_hi:[1,0]
	v_pk_mul_f32 v[44:45], v[44:45], v[4:5] op_sel_hi:[1,0]
	v_pk_mul_f32 v[46:47], v[46:47], v[4:5] op_sel_hi:[1,0]
	v_pk_mul_f32 v[16:17], v[16:17], v[4:5] op_sel_hi:[1,0]
	v_pk_mul_f32 v[18:19], v[18:19], v[4:5] op_sel_hi:[1,0]
	v_pk_mul_f32 v[20:21], v[20:21], v[4:5] op_sel_hi:[1,0]
	v_pk_mul_f32 v[22:23], v[22:23], v[4:5] op_sel_hi:[1,0]
	v_pk_mul_f32 v[24:25], v[24:25], v[4:5] op_sel_hi:[1,0]
	v_pk_mul_f32 v[26:27], v[26:27], v[4:5] op_sel_hi:[1,0]
	v_pk_mul_f32 v[28:29], v[28:29], v[4:5] op_sel_hi:[1,0]
	v_pk_mul_f32 v[30:31], v[30:31], v[4:5] op_sel_hi:[1,0]
	s_waitcnt vmcnt(0)
	v_permlane32_swap_b32 v192, v194
	v_permlane32_swap_b32 v193, v195
	v_permlane32_swap_b32 v196, v198
	v_permlane32_swap_b32 v197, v199
	v_permlane32_swap_b32 v200, v202
	v_permlane32_swap_b32 v201, v203
	v_permlane32_swap_b32 v204, v206
	v_permlane32_swap_b32 v205, v207
	v_lshlrev_b32_e32 v64, 16, v192
	v_and_b32_e32 v65, 0xffff0000, v192
	v_lshlrev_b32_e32 v66, 16, v193
	v_and_b32_e32 v67, 0xffff0000, v193
	v_lshlrev_b32_e32 v68, 16, v194
	v_and_b32_e32 v69, 0xffff0000, v194
	v_lshlrev_b32_e32 v70, 16, v195
	v_and_b32_e32 v71, 0xffff0000, v195
	v_lshlrev_b32_e32 v72, 16, v196
	v_and_b32_e32 v73, 0xffff0000, v196
	v_lshlrev_b32_e32 v74, 16, v197
	v_and_b32_e32 v75, 0xffff0000, v197
	v_lshlrev_b32_e32 v76, 16, v198
	v_and_b32_e32 v77, 0xffff0000, v198
	v_lshlrev_b32_e32 v78, 16, v199
	v_and_b32_e32 v79, 0xffff0000, v199
	v_pk_mul_f32 v[80:81], v[64:65], s[44:45]
	v_pk_mul_f32 v[82:83], v[66:67], s[44:45]
	v_pk_mul_f32 v[84:85], v[68:69], s[44:45]
	v_pk_mul_f32 v[86:87], v[70:71], s[44:45]
	v_pk_mul_f32 v[88:89], v[72:73], s[44:45]
	v_pk_mul_f32 v[90:91], v[74:75], s[44:45]
	v_pk_mul_f32 v[92:93], v[76:77], s[44:45]
	v_pk_mul_f32 v[94:95], v[78:79], s[44:45]
	v_exp_f32_e32 v80, v80
	v_exp_f32_e32 v81, v81
	v_exp_f32_e32 v82, v82
	v_exp_f32_e32 v83, v83
	v_exp_f32_e32 v84, v84
	v_exp_f32_e32 v85, v85
	v_exp_f32_e32 v86, v86
	v_exp_f32_e32 v87, v87
	v_exp_f32_e32 v88, v88
	v_exp_f32_e32 v89, v89
	v_exp_f32_e32 v90, v90
	v_exp_f32_e32 v91, v91
	v_exp_f32_e32 v92, v92
	v_exp_f32_e32 v93, v93
	v_exp_f32_e32 v94, v94
	v_exp_f32_e32 v95, v95
	v_pk_add_f32 v[80:81], v[80:81], s[46:47]
	v_pk_add_f32 v[82:83], v[82:83], s[46:47]
	v_pk_add_f32 v[84:85], v[84:85], s[46:47]
	v_pk_add_f32 v[86:87], v[86:87], s[46:47]
	v_pk_add_f32 v[88:89], v[88:89], s[46:47]
	v_pk_add_f32 v[90:91], v[90:91], s[46:47]
	v_pk_add_f32 v[92:93], v[92:93], s[46:47]
	v_pk_add_f32 v[94:95], v[94:95], s[46:47]
	v_rcp_f32_e32 v80, v80
	v_rcp_f32_e32 v81, v81
	v_rcp_f32_e32 v82, v82
	v_rcp_f32_e32 v83, v83
	v_rcp_f32_e32 v84, v84
	v_rcp_f32_e32 v85, v85
	v_rcp_f32_e32 v86, v86
	v_rcp_f32_e32 v87, v87
	v_rcp_f32_e32 v88, v88
	v_rcp_f32_e32 v89, v89
	v_rcp_f32_e32 v90, v90
	v_rcp_f32_e32 v91, v91
	v_rcp_f32_e32 v92, v92
	v_rcp_f32_e32 v93, v93
	v_rcp_f32_e32 v94, v94
	v_rcp_f32_e32 v95, v95
	v_pk_mul_f32 v[80:81], v[80:81], v[64:65]
	v_pk_mul_f32 v[82:83], v[82:83], v[66:67]
	v_pk_mul_f32 v[84:85], v[84:85], v[68:69]
	v_pk_mul_f32 v[86:87], v[86:87], v[70:71]
	v_pk_mul_f32 v[88:89], v[88:89], v[72:73]
	v_pk_mul_f32 v[90:91], v[90:91], v[74:75]
	v_pk_mul_f32 v[92:93], v[92:93], v[76:77]
	v_pk_mul_f32 v[94:95], v[94:95], v[78:79]
	v_pk_mul_f32 v[80:81], v[32:33], v[80:81]
	v_pk_mul_f32 v[82:83], v[34:35], v[82:83]
	v_pk_mul_f32 v[84:85], v[36:37], v[84:85]
	v_pk_mul_f32 v[86:87], v[38:39], v[86:87]
	v_pk_mul_f32 v[88:89], v[40:41], v[88:89]
	v_pk_mul_f32 v[90:91], v[42:43], v[90:91]
	v_pk_mul_f32 v[92:93], v[44:45], v[92:93]
	v_pk_mul_f32 v[94:95], v[46:47], v[94:95]
	v_cvt_pk_bf16_f32 v64, v80, v81
	v_cvt_pk_bf16_f32 v65, v82, v83
	v_cvt_pk_bf16_f32 v66, v84, v85
	v_cvt_pk_bf16_f32 v67, v86, v87
	v_cvt_pk_bf16_f32 v68, v88, v89
	v_cvt_pk_bf16_f32 v69, v90, v91
	v_cvt_pk_bf16_f32 v70, v92, v93
	v_cvt_pk_bf16_f32 v71, v94, v95
	s_nop 1
	v_permlane32_swap_b32 v64, v66
	v_permlane32_swap_b32 v65, v67
	v_permlane32_swap_b32 v68, v70
	v_permlane32_swap_b32 v69, v71
	global_store_dwordx4 v[98:99], v[64:67], off
	global_store_dwordx4 v[98:99], v[68:71], off offset:32
	s_nop 1
	v_lshlrev_b32_e32 v64, 16, v200
	v_and_b32_e32 v65, 0xffff0000, v200
	v_lshlrev_b32_e32 v66, 16, v201
	v_and_b32_e32 v67, 0xffff0000, v201
	v_lshlrev_b32_e32 v68, 16, v202
	v_and_b32_e32 v69, 0xffff0000, v202
	v_lshlrev_b32_e32 v70, 16, v203
	v_and_b32_e32 v71, 0xffff0000, v203
	v_lshlrev_b32_e32 v72, 16, v204
	v_and_b32_e32 v73, 0xffff0000, v204
	v_lshlrev_b32_e32 v74, 16, v205
	v_and_b32_e32 v75, 0xffff0000, v205
	v_lshlrev_b32_e32 v76, 16, v206
	v_and_b32_e32 v77, 0xffff0000, v206
	v_lshlrev_b32_e32 v78, 16, v207
	v_and_b32_e32 v79, 0xffff0000, v207
	v_pk_mul_f32 v[80:81], v[64:65], s[44:45]
	v_pk_mul_f32 v[82:83], v[66:67], s[44:45]
	v_pk_mul_f32 v[84:85], v[68:69], s[44:45]
	v_pk_mul_f32 v[86:87], v[70:71], s[44:45]
	v_pk_mul_f32 v[88:89], v[72:73], s[44:45]
	v_pk_mul_f32 v[90:91], v[74:75], s[44:45]
	v_pk_mul_f32 v[92:93], v[76:77], s[44:45]
	v_pk_mul_f32 v[94:95], v[78:79], s[44:45]
	v_exp_f32_e32 v80, v80
	v_exp_f32_e32 v81, v81
	v_exp_f32_e32 v82, v82
	v_exp_f32_e32 v83, v83
	v_exp_f32_e32 v84, v84
	v_exp_f32_e32 v85, v85
	v_exp_f32_e32 v86, v86
	v_exp_f32_e32 v87, v87
	v_exp_f32_e32 v88, v88
	v_exp_f32_e32 v89, v89
	v_exp_f32_e32 v90, v90
	v_exp_f32_e32 v91, v91
	v_exp_f32_e32 v92, v92
	v_exp_f32_e32 v93, v93
	v_exp_f32_e32 v94, v94
	v_exp_f32_e32 v95, v95
	v_pk_add_f32 v[80:81], v[80:81], s[46:47]
	v_pk_add_f32 v[82:83], v[82:83], s[46:47]
	v_pk_add_f32 v[84:85], v[84:85], s[46:47]
	v_pk_add_f32 v[86:87], v[86:87], s[46:47]
	v_pk_add_f32 v[88:89], v[88:89], s[46:47]
	v_pk_add_f32 v[90:91], v[90:91], s[46:47]
	v_pk_add_f32 v[92:93], v[92:93], s[46:47]
	v_pk_add_f32 v[94:95], v[94:95], s[46:47]
	v_rcp_f32_e32 v80, v80
	v_rcp_f32_e32 v81, v81
	v_rcp_f32_e32 v82, v82
	v_rcp_f32_e32 v83, v83
	v_rcp_f32_e32 v84, v84
	v_rcp_f32_e32 v85, v85
	v_rcp_f32_e32 v86, v86
	v_rcp_f32_e32 v87, v87
	v_rcp_f32_e32 v88, v88
	v_rcp_f32_e32 v89, v89
	v_rcp_f32_e32 v90, v90
	v_rcp_f32_e32 v91, v91
	v_rcp_f32_e32 v92, v92
	v_rcp_f32_e32 v93, v93
	v_rcp_f32_e32 v94, v94
	v_rcp_f32_e32 v95, v95
	v_pk_mul_f32 v[80:81], v[80:81], v[64:65]
	v_pk_mul_f32 v[82:83], v[82:83], v[66:67]
	v_pk_mul_f32 v[84:85], v[84:85], v[68:69]
	v_pk_mul_f32 v[86:87], v[86:87], v[70:71]
	v_pk_mul_f32 v[88:89], v[88:89], v[72:73]
	v_pk_mul_f32 v[90:91], v[90:91], v[74:75]
	v_pk_mul_f32 v[92:93], v[92:93], v[76:77]
	v_pk_mul_f32 v[94:95], v[94:95], v[78:79]
	v_pk_mul_f32 v[80:81], v[16:17], v[80:81]
	v_pk_mul_f32 v[82:83], v[18:19], v[82:83]
	v_pk_mul_f32 v[84:85], v[20:21], v[84:85]
	v_pk_mul_f32 v[86:87], v[22:23], v[86:87]
	v_pk_mul_f32 v[88:89], v[24:25], v[88:89]
	v_pk_mul_f32 v[90:91], v[26:27], v[90:91]
	v_pk_mul_f32 v[92:93], v[28:29], v[92:93]
	v_pk_mul_f32 v[94:95], v[30:31], v[94:95]
	v_cvt_pk_bf16_f32 v64, v80, v81
	v_cvt_pk_bf16_f32 v65, v82, v83
	v_cvt_pk_bf16_f32 v66, v84, v85
	v_cvt_pk_bf16_f32 v67, v86, v87
	v_cvt_pk_bf16_f32 v68, v88, v89
	v_cvt_pk_bf16_f32 v69, v90, v91
	v_cvt_pk_bf16_f32 v70, v92, v93
	v_cvt_pk_bf16_f32 v71, v94, v95
	s_nop 1
	v_permlane32_swap_b32 v64, v66
	v_permlane32_swap_b32 v65, v67
	v_permlane32_swap_b32 v68, v70
	v_permlane32_swap_b32 v69, v71
	global_store_dwordx4 v[98:99], v[64:67], off offset:64
	global_store_dwordx4 v[98:99], v[68:71], off offset:96
